# v40 + NSA rescale diamond: O accumulators rescaled in place, 64 common-path v_mov_b64 copies removed (8 sites), PV MFMAs read the old quads as SrcC; exact
# speedup vs baseline: 1.0115x; 1.0055x over previous
; template <int MODE>
; __device__ __forceinline__ void nsa_compute(int cur, int buf, int t, int hl, u64 mymask, const bf16x8 (&Qf)[2][2], f32x4 (&O)[4][2], float (&m)[2], float (&l)[2],
;                                             const float (&inv)[2], float* impw, char* lds) {
;     ...
; #pragma unroll
;   for (int s2 = 0; s2 < 2; ++s2) {
;     f32x4 S[2][2] = {};
;     bf16x8 kfr[2][2];
; #pragma unroll
;     for (int ks = 0; ks < 2; ++ks)
; #pragma unroll
;       for (int kk = 0; kk < 2; ++kk) kfr[ks][kk] = *(const bf16x8*)(kt + (32 * s2 + 16 * kk + fr) * 128 + (((ks * 4 + fq) ^ (fr & 7)) << 4));
;     __builtin_amdgcn_s_setprio(1);
; #pragma unroll
;     for (int ks = 0; ks < 2; ++ks)
; #pragma unroll
;       for (int kk = 0; kk < 2; ++kk)
; #pragma unroll
;         for (int r = 0; r < 2; ++r) S[kk][r] = mfma16(kfr[ks][kk], Qf[r][ks], S[kk][r]);
;     __builtin_amdgcn_s_setprio(0);
;     bf16x8 Pf[2];
;     float g1s[2] = {0.f, 0.f}, p3s[2] = {0.f, 0.f};
; #pragma unroll
;     for (int r = 0; r < 2; ++r) {
;       float sv[2][4];
; #pragma unroll
;       for (int kk = 0; kk < 2; ++kk)
; #pragma unroll
;         for (int e = 0; e < 4; ++e) {
;           const int off = 32 * s2 + 16 * kk + e;
;           int idx;
;           if (MODE <= 1) { idx = base - 16 * off; idx = idx > 0 ? idx : 0; } else idx = base - off;
;           sv[kk][e] = S[kk][r][e] * (0.125f * LOG2E) + tb[r * TS + idx];
;         }
;       float pv[2][4];
;       if (MODE == 1) {
; #pragma unroll
;         for (int kk = 0; kk < 2; ++kk)
; #pragma unroll
;           for (int e = 0; e < 4; ++e) pv[kk][e] = __builtin_amdgcn_exp2f(sv[kk][e] - m[r]) * inv[r];
; #pragma unroll
;         for (int kk = 0; kk < 2; ++kk) { g1s[kk] += pv[kk][0] + pv[kk][1] + pv[kk][2] + 0.5f * pv[kk][3]; p3s[kk] += 0.5f * pv[kk][3]; }
;       } else {
;         const float mxa = fmaxf(fmaxf(sv[0][0], sv[0][1]), sv[0][2]), mxb = fmaxf(fmaxf(sv[0][3], sv[1][0]), sv[1][1]);
;         float mx = fmaxf(fmaxf(fmaxf(sv[1][2], sv[1][3]), mxa), mxb);
;         if (MODE == 2) mx = selok ? mx : -__builtin_inff();
;         if (__any(mx > m[r] + 8.0f)) {
;           mx = fmaxf(mx, __shfl_xor(mx, 16)); mx = fmaxf(mx, __shfl_xor(mx, 32));
;           const float mn = fmaxf(m[r], mx), al = __builtin_amdgcn_exp2f(m[r] - mn);
;           m[r] = mn; l[r] *= al;
;           if (MODE != 0) {
; #pragma unroll
.LBB0_377:
	v_add_f32_e32 v104, 0, v113
	v_add_f32_e32 v104, v112, v104
	v_add_f32_e32 v104, v114, v104
	v_add_f32_e32 v104, v115, v104
	v_add_f32_e32 v104, v116, v104
	v_add_f32_e32 v104, v117, v104
	v_add_f32_e32 v104, v118, v104
	v_add_f32_e32 v104, v119, v104
	s_cmp_lt_i32 s16, 0
	v_add_f32_e32 v195, v195, v104
	s_cbranch_scc1 .LBB0_380
	v_mov_b32 v104, v179
	s_lshl_b32 s71, s46, 13
	v_lshrrev_b32_e32 v105, 4, v104
	v_bfe_u32 v120, v104, 4, 2
	v_and_b32_e32 v112, 7, v104
	v_and_b32_e32 v149, 15, v104
	v_bitop3_b32 v104, v105, v112, 3 bitop3:0x6c
	v_bitop3_b32 v112, v120, v112, 4 bitop3:0x36
	v_lshlrev_b32_e32 v146, 7, v149
	v_lshl_or_b32 v147, v104, 4, s71
	v_lshl_or_b32 v148, v112, 4, s71
	v_or_b32_e32 v108, v147, v146
	v_or_b32_e32 v116, v148, v146
	ds_read_b128 v[104:107], v108
	ds_read_b128 v[108:111], v108 offset:2048
	ds_read_b128 v[112:115], v116
	ds_read_b128 v[116:119], v116 offset:2048
	v_lshlrev_b32_e32 v150, 2, v120
	v_sub_u32_e32 v251, v180, v150
	v_lshl_add_u32 v251, v251, 2, v235
	s_lshl_b32 s16, s16, 8
	v_subrev_u32_e32 v250, s16, v251
	v_add_u32_e32 v249, 0xa00, v250
	ds_read2_b32 v[198:199], v250 offset0:63 offset1:64
	ds_read2_b32 v[200:201], v250 offset0:61 offset1:62
	ds_read2_b32 v[202:203], v250 offset0:47 offset1:48
	ds_read2_b32 v[204:205], v250 offset0:45 offset1:46
	ds_read2_b32 v[206:207], v249 offset0:63 offset1:64
	ds_read2_b32 v[208:209], v249 offset0:61 offset1:62
	ds_read2_b32 v[210:211], v249 offset0:47 offset1:48
	ds_read2_b32 v[236:237], v249 offset0:45 offset1:46
	s_setprio 1
	s_waitcnt lgkmcnt(11)
	v_mfma_f32_16x16x32_bf16 v[120:123], v[104:107], v[0:3], 0
	v_mfma_f32_16x16x32_bf16 v[104:107], v[104:107], v[8:11], 0
	s_waitcnt lgkmcnt(10)
	v_mfma_f32_16x16x32_bf16 v[128:131], v[108:111], v[0:3], 0
	v_mfma_f32_16x16x32_bf16 v[108:111], v[108:111], v[8:11], 0
	s_waitcnt lgkmcnt(9)
	v_mfma_f32_16x16x32_bf16 v[124:127], v[112:115], v[12:15], v[104:107]
	s_waitcnt lgkmcnt(8)
	v_mfma_f32_16x16x32_bf16 v[104:107], v[116:119], v[4:7], v[128:131]
	v_mfma_f32_16x16x32_bf16 v[116:119], v[116:119], v[12:15], v[108:111]
	v_mfma_f32_16x16x32_bf16 v[120:123], v[112:115], v[4:7], v[120:123]
	s_setprio 0
	s_nop 0
	v_sub_u32_e32 v108, v180, v150
	v_lshl_add_u32 v108, v108, 2, v235
	v_subrev_u32_e32 v154, s16, v108
	s_waitcnt lgkmcnt(7)
	s_nop 1
	v_fmamk_f32 v135, v120, 0x3e38aa3b, v199
	v_fmamk_f32 v134, v121, 0x3e38aa3b, v198
	s_waitcnt lgkmcnt(6)
	v_fmamk_f32 v133, v122, 0x3e38aa3b, v201
	v_fmamk_f32 v132, v123, 0x3e38aa3b, v200
	s_waitcnt lgkmcnt(5)
	v_fmamk_f32 v129, v104, 0x3e38aa3b, v203
	v_fmamk_f32 v128, v105, 0x3e38aa3b, v202
	s_waitcnt lgkmcnt(4)
	v_fmamk_f32 v131, v106, 0x3e38aa3b, v205
	v_fmamk_f32 v130, v107, 0x3e38aa3b, v204
	v_max3_f32 v104, v135, v134, v133
	v_max3_f32 v105, v132, v129, v128
	v_max_f32_e32 v106, v131, v130
	v_max3_f32 v104, v106, v104, v105
	v_add_f32_e32 v105, 0x41000000, v192
	v_cmp_gt_f32_e32 vcc, v104, v105
	s_cbranch_vccz .LBB0_381
	ds_bpermute_b32 v105, v233, v104
	v_max_f32_e32 v104, v104, v104
	v_mov_b32_e32 v137, v193
	v_mov_b32_e32 v197, v195
	s_waitcnt lgkmcnt(0)
	v_max_f32_e32 v105, v105, v105
	v_max_f32_e32 v104, v104, v105
	ds_bpermute_b32 v105, v234, v104
	s_waitcnt lgkmcnt(0)
	v_max3_f32 v136, v192, v104, v105
	v_sub_f32_e32 v104, v192, v136
	v_exp_f32_e32 v120, v104
	v_mov_b64_e32 v[192:193], v[136:137]
	v_mul_f32_e32 v196, v194, v120
	v_pk_mul_f32 v[90:91], v[90:91], v[120:121] op_sel_hi:[1,0]
	v_pk_mul_f32 v[88:89], v[88:89], v[120:121] op_sel_hi:[1,0]
	v_pk_mul_f32 v[102:103], v[102:103], v[120:121] op_sel_hi:[1,0]
	v_pk_mul_f32 v[100:101], v[100:101], v[120:121] op_sel_hi:[1,0]
	v_pk_mul_f32 v[94:95], v[94:95], v[120:121] op_sel_hi:[1,0]
	v_pk_mul_f32 v[92:93], v[92:93], v[120:121] op_sel_hi:[1,0]
	v_pk_mul_f32 v[82:83], v[82:83], v[120:121] op_sel_hi:[1,0]
	v_pk_mul_f32 v[80:81], v[80:81], v[120:121] op_sel_hi:[1,0]
	s_branch .LBB0_382

; template <int MODE>
; __device__ __forceinline__ void nsa_compute(int cur, int buf, int t, int hl, u64 mymask, const bf16x8 (&Qf)[2][2], f32x4 (&O)[4][2], float (&m)[2], float (&l)[2],
;                                             const float (&inv)[2], float* impw, char* lds) {
;     ...
;     for (int r = 0; r < 2; ++r) {
;       float sv[2][4];
; #pragma unroll
;       for (int kk = 0; kk < 2; ++kk)
; #pragma unroll
;         for (int e = 0; e < 4; ++e) {
;           const int off = 32 * s2 + 16 * kk + e;
;           int idx;
;           if (MODE <= 1) { idx = base - 16 * off; idx = idx > 0 ? idx : 0; } else idx = base - off;
;           sv[kk][e] = S[kk][r][e] * (0.125f * LOG2E) + tb[r * TS + idx];
;         }
;       float pv[2][4];
;       if (MODE == 1) {
; #pragma unroll
;         for (int kk = 0; kk < 2; ++kk)
; #pragma unroll
;           for (int e = 0; e < 4; ++e) pv[kk][e] = __builtin_amdgcn_exp2f(sv[kk][e] - m[r]) * inv[r];
; #pragma unroll
;         for (int kk = 0; kk < 2; ++kk) { g1s[kk] += pv[kk][0] + pv[kk][1] + pv[kk][2] + 0.5f * pv[kk][3]; p3s[kk] += 0.5f * pv[kk][3]; }
;       } else {
;         const float mxa = fmaxf(fmaxf(sv[0][0], sv[0][1]), sv[0][2]), mxb = fmaxf(fmaxf(sv[0][3], sv[1][0]), sv[1][1]);
;         float mx = fmaxf(fmaxf(fmaxf(sv[1][2], sv[1][3]), mxa), mxb);
;         if (MODE == 2) mx = selok ? mx : -__builtin_inff();
;         if (__any(mx > m[r] + 8.0f)) {
;           mx = fmaxf(mx, __shfl_xor(mx, 16)); mx = fmaxf(mx, __shfl_xor(mx, 32));
;           const float mn = fmaxf(m[r], mx), al = __builtin_amdgcn_exp2f(m[r] - mn);
;           m[r] = mn; l[r] *= al;
;           if (MODE != 0) {
; #pragma unroll
;             for (int df = 0; df < 4; ++df) O[df][r] *= al;
;           }
;         }
;         const float me = (MODE == 2) ? (selok ? m[r] : __builtin_inff()) : m[r];
;         float ps = 0.f;
; #pragma unroll
;         for (int kk = 0; kk < 2; ++kk)
; #pragma unroll
;           for (int e = 0; e < 4; ++e) { pv[kk][e] = __builtin_amdgcn_exp2f(sv[kk][e] - me); ps += pv[kk][e]; }
;         l[r] += ps;
.LBB0_381:
	v_mov_b64_e32 v[196:197], v[194:195]
	v_mov_b32_e32 v136, v192
.LBB0_382:
	v_sub_f32_e32 v135, v135, v136
	v_exp_f32_e32 v151, v135
	v_sub_f32_e32 v134, v134, v136
	v_exp_f32_e32 v152, v134
	v_sub_f32_e32 v133, v133, v136
	v_exp_f32_e32 v153, v133
	v_sub_f32_e32 v132, v132, v136
	v_exp_f32_e32 v155, v132
	v_sub_f32_e32 v129, v129, v136
	v_add_f32_e32 v135, 0, v151
	v_exp_f32_e32 v156, v129
	v_sub_f32_e32 v128, v128, v136
	v_add_f32_e32 v134, v152, v135
	v_exp_f32_e32 v157, v128
	v_add_f32_e32 v133, v153, v134
	v_add_f32_e32 v132, v155, v133
	v_add_f32_e32 v129, v156, v132
	v_add_f32_e32 v128, v157, v129
	v_sub_f32_e32 v129, v131, v136
	v_exp_f32_e32 v158, v129
	v_sub_f32_e32 v129, v130, v136
	v_exp_f32_e32 v159, v129
	v_add_f32_e32 v128, v158, v128
	v_add_f32_e32 v128, v159, v128
	v_add_f32_e32 v196, v196, v128
	s_waitcnt lgkmcnt(3)
	v_fmamk_f32 v135, v124, 0x3e38aa3b, v207
	v_fmamk_f32 v134, v125, 0x3e38aa3b, v206
	s_waitcnt lgkmcnt(2)
	v_fmamk_f32 v145, v126, 0x3e38aa3b, v209
	v_fmamk_f32 v144, v127, 0x3e38aa3b, v208
	s_waitcnt lgkmcnt(1)
	v_fmamk_f32 v133, v116, 0x3e38aa3b, v211
	v_fmamk_f32 v132, v117, 0x3e38aa3b, v210
	s_waitcnt lgkmcnt(0)
	v_fmamk_f32 v117, v118, 0x3e38aa3b, v237
	v_fmamk_f32 v116, v119, 0x3e38aa3b, v236
	v_max3_f32 v118, v135, v134, v145
	v_max3_f32 v119, v144, v133, v132
	v_max_f32_e32 v124, v117, v116
	v_max3_f32 v118, v124, v118, v119
	v_add_f32_e32 v119, 0x41000000, v193
	v_cmp_gt_f32_e32 vcc, v118, v119
	s_cbranch_vccz .LBB0_384
	ds_bpermute_b32 v119, v233, v118
	v_max_f32_e32 v118, v118, v118
	s_waitcnt lgkmcnt(0)
	v_max_f32_e32 v119, v119, v119
	v_max_f32_e32 v118, v118, v119
	ds_bpermute_b32 v119, v234, v118
	s_waitcnt lgkmcnt(0)
	v_max3_f32 v118, v193, v118, v119
	v_sub_f32_e32 v119, v193, v118
	v_exp_f32_e32 v140, v119
	v_mov_b32_e32 v193, v118
	v_mul_f32_e32 v197, v197, v140
	v_pk_mul_f32 v[98:99], v[98:99], v[140:141] op_sel_hi:[1,0]
	v_pk_mul_f32 v[96:97], v[96:97], v[140:141] op_sel_hi:[1,0]
	v_pk_mul_f32 v[86:87], v[86:87], v[140:141] op_sel_hi:[1,0]
	v_pk_mul_f32 v[84:85], v[84:85], v[140:141] op_sel_hi:[1,0]
	v_pk_mul_f32 v[78:79], v[78:79], v[140:141] op_sel_hi:[1,0]
	v_pk_mul_f32 v[76:77], v[76:77], v[140:141] op_sel_hi:[1,0]
	v_pk_mul_f32 v[74:75], v[74:75], v[140:141] op_sel_hi:[1,0]
	v_pk_mul_f32 v[72:73], v[72:73], v[140:141] op_sel_hi:[1,0]
	s_branch .LBB0_385
; template <int MODE>
; __device__ __forceinline__ void nsa_compute(int cur, int buf, int t, int hl, u64 mymask, const bf16x8 (&Qf)[2][2], f32x4 (&O)[4][2], float (&m)[2], float (&l)[2],
;                                             const float (&inv)[2], float* impw, char* lds) {
;     ...
; #pragma unroll
;     for (int ks = 0; ks < 2; ++ks)
; #pragma unroll
;       for (int kk = 0; kk < 2; ++kk) kfr[ks][kk] = *(const bf16x8*)(kt + (32 * s2 + 16 * kk + fr) * 128 + (((ks * 4 + fq) ^ (fr & 7)) << 4));
;     __builtin_amdgcn_s_setprio(1);
; #pragma unroll
;     for (int ks = 0; ks < 2; ++ks)
; #pragma unroll
;       for (int kk = 0; kk < 2; ++kk)
; #pragma unroll
;         for (int r = 0; r < 2; ++r) S[kk][r] = mfma16(kfr[ks][kk], Qf[r][ks], S[kk][r]);
;     __builtin_amdgcn_s_setprio(0);
;     bf16x8 Pf[2];
;     float g1s[2] = {0.f, 0.f}, p3s[2] = {0.f, 0.f};
; #pragma unroll
;     for (int r = 0; r < 2; ++r) {
;       float sv[2][4];
; #pragma unroll
;       for (int kk = 0; kk < 2; ++kk)
; #pragma unroll
;         for (int e = 0; e < 4; ++e) {
;     ...
;         const float me = (MODE == 2) ? (selok ? m[r] : __builtin_inff()) : m[r];
;         float ps = 0.f;
; #pragma unroll
;         for (int kk = 0; kk < 2; ++kk)
; #pragma unroll
;           for (int e = 0; e < 4; ++e) { pv[kk][e] = __builtin_amdgcn_exp2f(sv[kk][e] - me); ps += pv[kk][e]; }
;         l[r] += ps;
;       }
;       if (MODE != 0) {
;         const unsigned w0 = pk2(pv[0][0], pv[0][1]), w1 = pk2(pv[0][2], pv[0][3]), w2 = pk2(pv[1][0], pv[1][1]), w3 = pk2(pv[1][2], pv[1][3]);
;         u32x4 pw; pw.x = w0; pw.y = w1; pw.z = w2; pw.w = w3;
;         Pf[r] = __builtin_bit_cast(bf16x8, pw);
;       }
;     }
;     if (MODE != 0) {
;       bf16x8 vfr[4];
; #pragma unroll
;       for (int df = 0; df < 4; ++df) {
;         const bf16x4 va = *(const bf16x4*)(vt + (df * 16 + fr) * 68 + 32 * s2 + 4 * fq);
;         const bf16x4 vb = *(const bf16x4*)(vt + (df * 16 + fr) * 68 + 32 * s2 + 16 + 4 * fq);
;         bf16x8 vf; vf[0] = va[0]; vf[1] = va[1]; vf[2] = va[2]; vf[3] = va[3]; vf[4] = vb[0]; vf[5] = vb[1]; vf[6] = vb[2]; vf[7] = vb[3];
;         vfr[df] = vf;
;       }
;       __builtin_amdgcn_s_setprio(1);
; #pragma unroll
;       for (int df = 0; df < 4; ++df)
; #pragma unroll
;         for (int r = 0; r < 2; ++r) O[df][r] = mfma16(vfr[df], Pf[r], O[df][r]);
;       __builtin_amdgcn_s_setprio(0);
.LBB0_384:
.LBB0_385:
	v_sub_f32_e32 v119, v135, v193
	v_exp_f32_e32 v119, v119
	v_sub_f32_e32 v134, v134, v193
	v_exp_f32_e32 v134, v134
	v_sub_f32_e32 v145, v145, v193
	v_exp_f32_e32 v145, v145
	v_sub_f32_e32 v144, v144, v193
	v_exp_f32_e32 v144, v144
	v_sub_f32_e32 v133, v133, v193
	v_exp_f32_e32 v133, v133
	v_sub_f32_e32 v132, v132, v193
	v_add_f32_e32 v135, v134, v119
	v_exp_f32_e32 v132, v132
	v_sub_f32_e32 v117, v117, v193
	v_add_f32_e32 v135, v145, v135
	v_exp_f32_e32 v117, v117
	v_sub_f32_e32 v116, v116, v193
	v_add_f32_e32 v135, v144, v135
	v_exp_f32_e32 v116, v116
	v_add_f32_e32 v135, v133, v135
	v_add_f32_e32 v135, v132, v135
	v_add_f32_e32 v135, v117, v135
	s_lshl_b32 s16, s46, 9
	v_add_f32_e32 v118, v116, v135
	v_cvt_pk_bf16_f32 v167, v117, v116
	v_mul_u32_u24_e32 v116, 0x44, v149
	s_add_i32 s72, s71, s16
	v_lshlrev_b32_e32 v116, 1, v116
	v_lshlrev_b32_e32 v117, 1, v150
	v_add3_u32 v116, s72, v116, v117
	v_cvt_pk_bf16_f32 v161, v153, v155
	v_cvt_pk_bf16_f32 v162, v156, v157
	v_add_u32_e32 v155, 0x4000, v116
	v_add_u32_e32 v156, 0x4800, v116
	v_cvt_pk_bf16_f32 v160, v151, v152
	v_cvt_pk_bf16_f32 v163, v158, v159
	v_cvt_pk_bf16_f32 v164, v119, v134
	v_cvt_pk_bf16_f32 v166, v133, v132
	ds_read2_b64 v[132:135], v155 offset1:4
	ds_read2_b64 v[150:153], v156 offset0:16 offset1:20
	v_add_u32_e32 v157, 0x5000, v116
	v_add_u32_e32 v158, 0x5800, v116
	ds_read2_b64 v[168:171], v157 offset0:32 offset1:36
	ds_read2_b64 v[172:175], v158 offset0:48 offset1:52
	v_add_f32_e32 v197, v197, v118
	v_cvt_pk_bf16_f32 v165, v145, v144
	s_setprio 1
	s_waitcnt lgkmcnt(3)
	v_mfma_f32_16x16x32_bf16 v[116:119], v[132:135], v[160:163], v[88:91]
	v_mfma_f32_16x16x32_bf16 v[132:135], v[132:135], v[164:167], v[96:99]
	s_waitcnt lgkmcnt(2)
	v_mfma_f32_16x16x32_bf16 v[112:115], v[150:153], v[160:163], v[100:103]
	v_mfma_f32_16x16x32_bf16 v[128:131], v[150:153], v[164:167], v[84:87]
	s_waitcnt lgkmcnt(1)
	v_mfma_f32_16x16x32_bf16 v[108:111], v[168:171], v[160:163], v[92:95]
	v_mfma_f32_16x16x32_bf16 v[124:127], v[168:171], v[164:167], v[76:79]
	s_waitcnt lgkmcnt(0)
	v_mfma_f32_16x16x32_bf16 v[104:107], v[172:175], v[160:163], v[80:83]
	v_mfma_f32_16x16x32_bf16 v[120:123], v[172:175], v[164:167], v[72:75]
	s_setprio 0
	s_nop 1
	v_add_u32_e32 v140, v147, v146
	v_add_u32_e32 v148, v148, v146
	ds_read_b128 v[136:139], v140 offset:4096
	ds_read_b128 v[140:143], v140 offset:6144
	ds_read_b128 v[144:147], v148 offset:4096
	ds_read_b128 v[148:151], v148 offset:6144
	v_add_u32_e32 v251, 0xa00, v154
	ds_read2_b32 v[202:203], v154 offset0:31 offset1:32
	ds_read2_b32 v[204:205], v154 offset0:29 offset1:30
	ds_read2_b32 v[206:207], v154 offset0:15 offset1:16
	ds_read2_b32 v[208:209], v154 offset0:13 offset1:14
	ds_read2_b32 v[210:211], v251 offset0:31 offset1:32
	ds_read2_b32 v[236:237], v251 offset0:29 offset1:30
	ds_read2_b32 v[238:239], v251 offset0:15 offset1:16
	ds_read2_b32 v[240:241], v251 offset0:13 offset1:14
	s_setprio 1
	s_waitcnt lgkmcnt(11)
	v_mfma_f32_16x16x32_bf16 v[160:163], v[136:139], v[0:3], 0
	v_mfma_f32_16x16x32_bf16 v[136:139], v[136:139], v[8:11], 0
	s_waitcnt lgkmcnt(10)
	v_mfma_f32_16x16x32_bf16 v[168:171], v[140:143], v[8:11], 0
	v_mfma_f32_16x16x32_bf16 v[164:167], v[140:143], v[0:3], 0
	s_waitcnt lgkmcnt(9)
	v_mfma_f32_16x16x32_bf16 v[160:163], v[144:147], v[4:7], v[160:163]
	v_mfma_f32_16x16x32_bf16 v[140:143], v[144:147], v[12:15], v[136:139]
	s_waitcnt lgkmcnt(8)
	v_mfma_f32_16x16x32_bf16 v[136:139], v[148:151], v[12:15], v[168:171]
	v_mfma_f32_16x16x32_bf16 v[164:167], v[148:151], v[4:7], v[164:167]
	s_setprio 0
	s_waitcnt lgkmcnt(7)
	s_nop 1
	v_fmamk_f32 v160, v160, 0x3e38aa3b, v203
	v_fmamk_f32 v150, v161, 0x3e38aa3b, v202
	s_waitcnt lgkmcnt(6)
	v_fmamk_f32 v159, v162, 0x3e38aa3b, v205
	v_fmamk_f32 v148, v163, 0x3e38aa3b, v204
	s_waitcnt lgkmcnt(5)
	v_fmamk_f32 v151, v164, 0x3e38aa3b, v207
	v_fmamk_f32 v146, v165, 0x3e38aa3b, v206
	s_waitcnt lgkmcnt(4)
	v_fmamk_f32 v145, v166, 0x3e38aa3b, v209
	v_fmamk_f32 v144, v167, 0x3e38aa3b, v208
	v_max3_f32 v147, v160, v150, v159
	v_max3_f32 v149, v148, v151, v146
	v_max_f32_e32 v152, v145, v144
	v_max3_f32 v147, v152, v147, v149
	v_add_f32_e32 v149, 0x41000000, v192
	v_cmp_gt_f32_e32 vcc, v147, v149
	s_cbranch_vccz .LBB0_387
	ds_bpermute_b32 v149, v233, v147
	v_max_f32_e32 v147, v147, v147
	v_mov_b32_e32 v153, v193
	s_waitcnt lgkmcnt(0)
	v_max_f32_e32 v149, v149, v149
	v_max_f32_e32 v147, v147, v149
	ds_bpermute_b32 v149, v234, v147
	s_waitcnt lgkmcnt(0)
	v_max3_f32 v152, v192, v147, v149
	v_sub_f32_e32 v147, v192, v152
	v_exp_f32_e32 v162, v147
	v_mov_b64_e32 v[192:193], v[152:153]
	v_mul_f32_e32 v196, v196, v162
	v_pk_mul_f32 v[118:119], v[118:119], v[162:163] op_sel_hi:[1,0]
	v_pk_mul_f32 v[116:117], v[116:117], v[162:163] op_sel_hi:[1,0]
	v_pk_mul_f32 v[114:115], v[114:115], v[162:163] op_sel_hi:[1,0]
	v_pk_mul_f32 v[112:113], v[112:113], v[162:163] op_sel_hi:[1,0]
	v_pk_mul_f32 v[110:111], v[110:111], v[162:163] op_sel_hi:[1,0]
	v_pk_mul_f32 v[108:109], v[108:109], v[162:163] op_sel_hi:[1,0]
	v_pk_mul_f32 v[106:107], v[106:107], v[162:163] op_sel_hi:[1,0]
	v_pk_mul_f32 v[104:105], v[104:105], v[162:163] op_sel_hi:[1,0]
	s_branch .LBB0_388

; template <int MODE>
; __device__ __forceinline__ void nsa_compute(int cur, int buf, int t, int hl, u64 mymask, const bf16x8 (&Qf)[2][2], f32x4 (&O)[4][2], float (&m)[2], float (&l)[2],
;                                             const float (&inv)[2], float* impw, char* lds) {
;     ...
; #pragma unroll
;   for (int s2 = 0; s2 < 2; ++s2) {
;     f32x4 S[2][2] = {};
;     bf16x8 kfr[2][2];
; #pragma unroll
;     for (int ks = 0; ks < 2; ++ks)
; #pragma unroll
;       for (int kk = 0; kk < 2; ++kk) kfr[ks][kk] = *(const bf16x8*)(kt + (32 * s2 + 16 * kk + fr) * 128 + (((ks * 4 + fq) ^ (fr & 7)) << 4));
;     __builtin_amdgcn_s_setprio(1);
; #pragma unroll
;     for (int ks = 0; ks < 2; ++ks)
; #pragma unroll
;       for (int kk = 0; kk < 2; ++kk)
; #pragma unroll
;         for (int r = 0; r < 2; ++r) S[kk][r] = mfma16(kfr[ks][kk], Qf[r][ks], S[kk][r]);
;     __builtin_amdgcn_s_setprio(0);
;     bf16x8 Pf[2];
;     float g1s[2] = {0.f, 0.f}, p3s[2] = {0.f, 0.f};
; #pragma unroll
;     for (int r = 0; r < 2; ++r) {
;       float sv[2][4];
; #pragma unroll
;       for (int kk = 0; kk < 2; ++kk)
; #pragma unroll
;         for (int e = 0; e < 4; ++e) {
;           const int off = 32 * s2 + 16 * kk + e;
;           int idx;
;           if (MODE <= 1) { idx = base - 16 * off; idx = idx > 0 ? idx : 0; } else idx = base - off;
;           sv[kk][e] = S[kk][r][e] * (0.125f * LOG2E) + tb[r * TS + idx];
;         }
;       float pv[2][4];
;       if (MODE == 1) {
; #pragma unroll
;         for (int kk = 0; kk < 2; ++kk)
; #pragma unroll
;           for (int e = 0; e < 4; ++e) pv[kk][e] = __builtin_amdgcn_exp2f(sv[kk][e] - m[r]) * inv[r];
; #pragma unroll
;         for (int kk = 0; kk < 2; ++kk) { g1s[kk] += pv[kk][0] + pv[kk][1] + pv[kk][2] + 0.5f * pv[kk][3]; p3s[kk] += 0.5f * pv[kk][3]; }
;       } else {
;         const float mxa = fmaxf(fmaxf(sv[0][0], sv[0][1]), sv[0][2]), mxb = fmaxf(fmaxf(sv[0][3], sv[1][0]), sv[1][1]);
;         float mx = fmaxf(fmaxf(fmaxf(sv[1][2], sv[1][3]), mxa), mxb);
;         if (MODE == 2) mx = selok ? mx : -__builtin_inff();
;         if (__any(mx > m[r] + 8.0f)) {
;           mx = fmaxf(mx, __shfl_xor(mx, 16)); mx = fmaxf(mx, __shfl_xor(mx, 32));
;           const float mn = fmaxf(m[r], mx), al = __builtin_amdgcn_exp2f(m[r] - mn);
;           m[r] = mn; l[r] *= al;
;           if (MODE != 0) {
; #pragma unroll
.LBB0_395:
	v_add_f32_e32 v104, 0, v168
	v_add_f32_e32 v104, v169, v104
	v_add_f32_e32 v104, v170, v104
	v_add_f32_e32 v104, v171, v104
	v_add_f32_e32 v104, v172, v104
	v_add_f32_e32 v104, v173, v104
	v_add_f32_e32 v104, v174, v104
	v_add_f32_e32 v104, v175, v104
	v_add_f32_e32 v197, v197, v104
	s_mov_b64 s[30:31], -1
	s_cmp_lt_i32 s42, 0
	s_mov_b64 s[36:37], -1
	s_cbranch_scc1 .LBB0_413
	v_mov_b32 v104, v179
	s_nop 0
	v_lshrrev_b32_e32 v105, 4, v104
	v_bfe_u32 v112, v104, 4, 2
	v_and_b32_e32 v113, 7, v104
	v_and_b32_e32 v200, 15, v104
	v_lshlrev_b32_e32 v201, 2, v112
	v_bitop3_b32 v104, v105, v113, 3 bitop3:0x6c
	v_bitop3_b32 v112, v112, v113, 4 bitop3:0x36
	v_lshlrev_b32_e32 v114, 7, v200
	v_lshl_add_u32 v104, v104, 4, s64
	v_lshl_add_u32 v112, v112, 4, s64
	v_add_u32_e32 v198, v104, v114
	v_add_u32_e32 v199, v112, v114
	ds_read_b128 v[104:107], v198
	ds_read_b128 v[108:111], v198 offset:2048
	ds_read_b128 v[112:115], v199
	ds_read_b128 v[116:119], v199 offset:2048
	s_setprio 1
	s_waitcnt lgkmcnt(3)
	v_mfma_f32_16x16x32_bf16 v[120:123], v[104:107], v[0:3], 0
	v_mfma_f32_16x16x32_bf16 v[104:107], v[104:107], v[8:11], 0
	s_waitcnt lgkmcnt(2)
	v_mfma_f32_16x16x32_bf16 v[128:131], v[108:111], v[0:3], 0
	v_mfma_f32_16x16x32_bf16 v[108:111], v[108:111], v[8:11], 0
	s_waitcnt lgkmcnt(1)
	v_mfma_f32_16x16x32_bf16 v[168:171], v[112:115], v[4:7], v[120:123]
	v_mfma_f32_16x16x32_bf16 v[124:127], v[112:115], v[12:15], v[104:107]
	s_waitcnt lgkmcnt(0)
	v_mfma_f32_16x16x32_bf16 v[104:107], v[116:119], v[4:7], v[128:131]
	v_mfma_f32_16x16x32_bf16 v[120:123], v[116:119], v[12:15], v[108:111]
	s_setprio 0
	s_nop 1
	v_sub_u32_e32 v108, v180, v201
	v_lshl_add_u32 v108, v108, 2, v235
	s_lshl_b32 s30, s42, 8
	v_subrev_u32_e32 v176, s30, v108
	ds_read2_b32 v[134:135], v176 offset0:63 offset1:64
	ds_read2_b32 v[132:133], v176 offset0:61 offset1:62
	ds_read2_b32 v[128:129], v176 offset0:47 offset1:48
	ds_read2_b32 v[130:131], v176 offset0:45 offset1:46
	s_waitcnt lgkmcnt(3)
	v_fmamk_f32 v135, v168, 0x3e38aa3b, v135
	v_fmac_f32_e32 v134, 0x3e38aa3b, v169
	s_waitcnt lgkmcnt(2)
	v_fmamk_f32 v133, v170, 0x3e38aa3b, v133
	v_fmac_f32_e32 v132, 0x3e38aa3b, v171
	s_waitcnt lgkmcnt(1)
	v_fmamk_f32 v129, v104, 0x3e38aa3b, v129
	v_fmac_f32_e32 v128, 0x3e38aa3b, v105
	s_waitcnt lgkmcnt(0)
	v_fmamk_f32 v131, v106, 0x3e38aa3b, v131
	v_fmac_f32_e32 v130, 0x3e38aa3b, v107
	v_max3_f32 v104, v135, v134, v133
	v_max3_f32 v105, v132, v129, v128
	v_max_f32_e32 v106, v131, v130
	v_max3_f32 v104, v106, v104, v105
	v_add_f32_e32 v105, 0x41000000, v192
	v_cmp_gt_f32_e32 vcc, v104, v105
	s_cbranch_vccz .LBB0_398
	ds_bpermute_b32 v105, v233, v104
	v_max_f32_e32 v104, v104, v104
	v_mov_b32_e32 v169, v193
	v_mov_b32_e32 v191, v197
	s_waitcnt lgkmcnt(0)
	v_max_f32_e32 v105, v105, v105
	v_max_f32_e32 v104, v104, v105
	ds_bpermute_b32 v105, v234, v104
	s_waitcnt lgkmcnt(0)
	v_max3_f32 v168, v192, v104, v105
	v_sub_f32_e32 v104, v192, v168
	v_exp_f32_e32 v116, v104
	v_mov_b64_e32 v[192:193], v[168:169]
	v_mul_f32_e32 v190, v196, v116
	v_pk_mul_f32 v[138:139], v[138:139], v[116:117] op_sel_hi:[1,0]
	v_pk_mul_f32 v[136:137], v[136:137], v[116:117] op_sel_hi:[1,0]
	v_pk_mul_f32 v[158:159], v[158:159], v[116:117] op_sel_hi:[1,0]
	v_pk_mul_f32 v[156:157], v[156:157], v[116:117] op_sel_hi:[1,0]
	v_pk_mul_f32 v[162:163], v[162:163], v[116:117] op_sel_hi:[1,0]
	v_pk_mul_f32 v[160:161], v[160:161], v[116:117] op_sel_hi:[1,0]
	v_pk_mul_f32 v[166:167], v[166:167], v[116:117] op_sel_hi:[1,0]
	v_pk_mul_f32 v[164:165], v[164:165], v[116:117] op_sel_hi:[1,0]
	s_branch .LBB0_399
.LBB0_398:
	v_mov_b64_e32 v[190:191], v[196:197]
	v_mov_b32_e32 v168, v192
.LBB0_399:
	v_sub_f32_e32 v135, v135, v168
	v_exp_f32_e32 v202, v135
	v_sub_f32_e32 v134, v134, v168
	v_exp_f32_e32 v203, v134
	v_sub_f32_e32 v133, v133, v168
	v_exp_f32_e32 v204, v133
	v_sub_f32_e32 v132, v132, v168
	v_exp_f32_e32 v205, v132
	v_sub_f32_e32 v129, v129, v168
	v_add_f32_e32 v135, 0, v202
	v_exp_f32_e32 v206, v129
	v_sub_f32_e32 v128, v128, v168
	v_add_f32_e32 v134, v203, v135
	v_exp_f32_e32 v207, v128
	v_add_f32_e32 v133, v204, v134
	v_add_f32_e32 v132, v205, v133
	v_add_f32_e32 v129, v206, v132
	v_add_f32_e32 v128, v207, v129
	v_sub_f32_e32 v129, v131, v168
	v_exp_f32_e32 v236, v129
	v_sub_f32_e32 v129, v130, v168
	v_exp_f32_e32 v237, v129
	v_add_f32_e32 v128, v236, v128
	v_add_f32_e32 v128, v237, v128
	v_add_f32_e32 v190, v190, v128
	v_add_u32_e32 v128, 0xafc, v176
	ds_read2_b32 v[172:173], v128 offset1:1
	s_waitcnt lgkmcnt(0)
	v_fmamk_f32 v173, v124, 0x3e38aa3b, v173
	v_add_u32_e32 v124, 0xaf4, v176
	ds_read2_b32 v[174:175], v124 offset1:1
	v_add_u32_e32 v124, 0xabc, v176
	v_fmac_f32_e32 v172, 0x3e38aa3b, v125
	ds_read2_b32 v[124:125], v124 offset1:1
	s_waitcnt lgkmcnt(1)
	v_fmamk_f32 v175, v126, 0x3e38aa3b, v175
	v_fmac_f32_e32 v174, 0x3e38aa3b, v127
	s_waitcnt lgkmcnt(0)
	v_fmamk_f32 v125, v120, 0x3e38aa3b, v125
	v_add_u32_e32 v120, 0xab4, v176
	ds_read2_b32 v[126:127], v120 offset1:1
	v_fmac_f32_e32 v124, 0x3e38aa3b, v121
	v_max3_f32 v120, v173, v172, v175
	v_max3_f32 v121, v174, v125, v124
	s_waitcnt lgkmcnt(0)
	v_fmamk_f32 v127, v122, 0x3e38aa3b, v127
	v_fmac_f32_e32 v126, 0x3e38aa3b, v123
	v_max_f32_e32 v122, v127, v126
	v_max3_f32 v120, v122, v120, v121
	v_add_f32_e32 v121, 0x41000000, v193
	v_cmp_gt_f32_e32 vcc, v120, v121
	s_cbranch_vccz .LBB0_401
	ds_bpermute_b32 v121, v233, v120
	v_max_f32_e32 v120, v120, v120
	s_waitcnt lgkmcnt(0)
	v_max_f32_e32 v121, v121, v121
	v_max_f32_e32 v120, v120, v121
	ds_bpermute_b32 v121, v234, v120
	s_waitcnt lgkmcnt(0)
	v_max3_f32 v238, v193, v120, v121
	v_sub_f32_e32 v120, v193, v238
	v_exp_f32_e32 v168, v120
	v_mov_b32_e32 v193, v238
	v_mul_f32_e32 v191, v191, v168
	v_pk_mul_f32 v[142:143], v[142:143], v[168:169] op_sel_hi:[1,0]
	v_pk_mul_f32 v[140:141], v[140:141], v[168:169] op_sel_hi:[1,0]
	v_pk_mul_f32 v[146:147], v[146:147], v[168:169] op_sel_hi:[1,0]
	v_pk_mul_f32 v[144:145], v[144:145], v[168:169] op_sel_hi:[1,0]
	v_pk_mul_f32 v[150:151], v[150:151], v[168:169] op_sel_hi:[1,0]
	v_pk_mul_f32 v[148:149], v[148:149], v[168:169] op_sel_hi:[1,0]
	v_pk_mul_f32 v[154:155], v[154:155], v[168:169] op_sel_hi:[1,0]
	v_pk_mul_f32 v[152:153], v[152:153], v[168:169] op_sel_hi:[1,0]
	s_branch .LBB0_402
; template <int MODE>
; __device__ __forceinline__ void nsa_compute(int cur, int buf, int t, int hl, u64 mymask, const bf16x8 (&Qf)[2][2], f32x4 (&O)[4][2], float (&m)[2], float (&l)[2],
;                                             const float (&inv)[2], float* impw, char* lds) {
;     ...
; #pragma unroll
;     for (int ks = 0; ks < 2; ++ks)
; #pragma unroll
;       for (int kk = 0; kk < 2; ++kk) kfr[ks][kk] = *(const bf16x8*)(kt + (32 * s2 + 16 * kk + fr) * 128 + (((ks * 4 + fq) ^ (fr & 7)) << 4));
;     __builtin_amdgcn_s_setprio(1);
; #pragma unroll
;     for (int ks = 0; ks < 2; ++ks)
; #pragma unroll
;       for (int kk = 0; kk < 2; ++kk)
; #pragma unroll
;         for (int r = 0; r < 2; ++r) S[kk][r] = mfma16(kfr[ks][kk], Qf[r][ks], S[kk][r]);
;     __builtin_amdgcn_s_setprio(0);
;     bf16x8 Pf[2];
;     float g1s[2] = {0.f, 0.f}, p3s[2] = {0.f, 0.f};
; #pragma unroll
;     for (int r = 0; r < 2; ++r) {
;       float sv[2][4];
; #pragma unroll
;       for (int kk = 0; kk < 2; ++kk)
; #pragma unroll
;         for (int e = 0; e < 4; ++e) {
;     ...
;         const float me = (MODE == 2) ? (selok ? m[r] : __builtin_inff()) : m[r];
;         float ps = 0.f;
; #pragma unroll
;         for (int kk = 0; kk < 2; ++kk)
; #pragma unroll
;           for (int e = 0; e < 4; ++e) { pv[kk][e] = __builtin_amdgcn_exp2f(sv[kk][e] - me); ps += pv[kk][e]; }
;         l[r] += ps;
;       }
;       if (MODE != 0) {
;         const unsigned w0 = pk2(pv[0][0], pv[0][1]), w1 = pk2(pv[0][2], pv[0][3]), w2 = pk2(pv[1][0], pv[1][1]), w3 = pk2(pv[1][2], pv[1][3]);
;         u32x4 pw; pw.x = w0; pw.y = w1; pw.z = w2; pw.w = w3;
;         Pf[r] = __builtin_bit_cast(bf16x8, pw);
;       }
;     }
;     if (MODE != 0) {
;       bf16x8 vfr[4];
; #pragma unroll
;       for (int df = 0; df < 4; ++df) {
;         const bf16x4 va = *(const bf16x4*)(vt + (df * 16 + fr) * 68 + 32 * s2 + 4 * fq);
;         const bf16x4 vb = *(const bf16x4*)(vt + (df * 16 + fr) * 68 + 32 * s2 + 16 + 4 * fq);
;         bf16x8 vf; vf[0] = va[0]; vf[1] = va[1]; vf[2] = va[2]; vf[3] = va[3]; vf[4] = vb[0]; vf[5] = vb[1]; vf[6] = vb[2]; vf[7] = vb[3];
;         vfr[df] = vf;
;       }
;       __builtin_amdgcn_s_setprio(1);
; #pragma unroll
;       for (int df = 0; df < 4; ++df)
; #pragma unroll
;         for (int r = 0; r < 2; ++r) O[df][r] = mfma16(vfr[df], Pf[r], O[df][r]);
;       __builtin_amdgcn_s_setprio(0);
.LBB0_401:
.LBB0_402:
	v_sub_f32_e32 v173, v173, v193
	v_exp_f32_e32 v173, v173
	v_sub_f32_e32 v172, v172, v193
	v_exp_f32_e32 v172, v172
	v_sub_f32_e32 v175, v175, v193
	v_exp_f32_e32 v175, v175
	v_sub_f32_e32 v174, v174, v193
	v_exp_f32_e32 v174, v174
	v_sub_f32_e32 v125, v125, v193
	v_cvt_pk_bf16_f32 v202, v202, v203
	v_cvt_pk_bf16_f32 v203, v204, v205
	v_cvt_pk_bf16_f32 v204, v206, v207
	v_exp_f32_e32 v125, v125
	v_sub_f32_e32 v124, v124, v193
	v_add_f32_e32 v206, v172, v173
	v_exp_f32_e32 v124, v124
	v_add_f32_e32 v206, v175, v206
	v_add_f32_e32 v206, v174, v206
	v_sub_f32_e32 v127, v127, v193
	v_add_f32_e32 v206, v125, v206
	v_exp_f32_e32 v127, v127
	v_sub_f32_e32 v126, v126, v193
	v_add_f32_e32 v206, v124, v206
	v_exp_f32_e32 v126, v126
	v_cvt_pk_bf16_f32 v172, v173, v172
	v_cvt_pk_bf16_f32 v173, v175, v174
	v_cvt_pk_bf16_f32 v174, v125, v124
	v_mul_u32_u24_e32 v124, 0x44, v200
	v_lshlrev_b32_e32 v124, 1, v124
	v_lshlrev_b32_e32 v125, 1, v201
	v_add3_u32 v200, s43, v124, v125
	v_cvt_pk_bf16_f32 v205, v236, v237
	v_add_f32_e32 v206, v127, v206
	v_add_u32_e32 v236, 0x4000, v200
	v_add_u32_e32 v237, 0x4800, v200
	v_add_f32_e32 v206, v126, v206
	v_cvt_pk_bf16_f32 v175, v127, v126
	ds_read2_b64 v[124:127], v236 offset1:4
	ds_read2_b64 v[240:243], v237 offset0:16 offset1:20
	v_add_u32_e32 v238, 0x5000, v200
	v_add_u32_e32 v239, 0x5800, v200
	ds_read2_b64 v[244:247], v238 offset0:32 offset1:36
	ds_read2_b64 v[248:251], v239 offset0:48 offset1:52
	v_add_f32_e32 v191, v191, v206
	s_setprio 1
	s_waitcnt lgkmcnt(3)
	v_mfma_f32_16x16x32_bf16 v[104:107], v[124:127], v[202:205], v[136:139]
	v_mfma_f32_16x16x32_bf16 v[124:127], v[124:127], v[172:175], v[140:143]
	s_waitcnt lgkmcnt(2)
	v_mfma_f32_16x16x32_bf16 v[108:111], v[240:243], v[202:205], v[156:159]
	v_mfma_f32_16x16x32_bf16 v[128:131], v[240:243], v[172:175], v[144:147]
	s_waitcnt lgkmcnt(1)
	v_mfma_f32_16x16x32_bf16 v[112:115], v[244:247], v[202:205], v[160:163]
	v_mfma_f32_16x16x32_bf16 v[132:135], v[244:247], v[172:175], v[148:151]
	s_waitcnt lgkmcnt(0)
	v_mfma_f32_16x16x32_bf16 v[120:123], v[248:251], v[202:205], v[164:167]
	v_mfma_f32_16x16x32_bf16 v[168:171], v[248:251], v[172:175], v[152:155]
	s_setprio 0
	s_nop 0
	ds_read_b128 v[116:119], v198 offset:4096
	ds_read_b128 v[172:175], v198 offset:6144
	ds_read_b128 v[200:203], v199 offset:4096
	ds_read_b128 v[204:207], v199 offset:6144
	s_setprio 1
	s_waitcnt lgkmcnt(3)
	v_mfma_f32_16x16x32_bf16 v[240:243], v[116:119], v[0:3], 0
	v_mfma_f32_16x16x32_bf16 v[116:119], v[116:119], v[8:11], 0
	s_waitcnt lgkmcnt(2)
	v_mfma_f32_16x16x32_bf16 v[248:251], v[172:175], v[8:11], 0
	v_mfma_f32_16x16x32_bf16 v[244:247], v[172:175], v[0:3], 0
	s_waitcnt lgkmcnt(1)
	v_mfma_f32_16x16x32_bf16 v[172:175], v[200:203], v[12:15], v[116:119]
	s_waitcnt lgkmcnt(0)
	v_mfma_f32_16x16x32_bf16 v[116:119], v[204:207], v[12:15], v[248:251]
	v_mfma_f32_16x16x32_bf16 v[208:211], v[200:203], v[4:7], v[240:243]
	v_mfma_f32_16x16x32_bf16 v[242:245], v[204:207], v[4:7], v[244:247]
	s_setprio 0
	ds_read2_b32 v[204:205], v176 offset0:31 offset1:32
	ds_read2_b32 v[202:203], v176 offset0:29 offset1:30
	ds_read2_b32 v[200:201], v176 offset0:15 offset1:16
	ds_read2_b32 v[198:199], v176 offset0:13 offset1:14
	s_waitcnt lgkmcnt(3)
	s_nop 0
	v_fmamk_f32 v241, v208, 0x3e38aa3b, v205
	v_fmac_f32_e32 v204, 0x3e38aa3b, v209
	s_waitcnt lgkmcnt(2)
	v_fmamk_f32 v240, v210, 0x3e38aa3b, v203
	v_fmac_f32_e32 v202, 0x3e38aa3b, v211
	s_waitcnt lgkmcnt(1)
	v_fmamk_f32 v205, v242, 0x3e38aa3b, v201
	v_fmac_f32_e32 v200, 0x3e38aa3b, v243
	s_waitcnt lgkmcnt(0)
	v_fmamk_f32 v199, v244, 0x3e38aa3b, v199
	v_fmac_f32_e32 v198, 0x3e38aa3b, v245
	v_max3_f32 v201, v241, v204, v240
	v_max3_f32 v203, v202, v205, v200
	v_max_f32_e32 v206, v199, v198
	v_max3_f32 v201, v206, v201, v203
	v_add_f32_e32 v203, 0x41000000, v192
	v_cmp_gt_f32_e32 vcc, v201, v203
	s_cbranch_vccz .LBB0_404
	ds_bpermute_b32 v203, v233, v201
	v_max_f32_e32 v201, v201, v201
	v_mov_b32_e32 v207, v193
	s_waitcnt lgkmcnt(0)
	v_max_f32_e32 v203, v203, v203
	v_max_f32_e32 v201, v201, v203
	ds_bpermute_b32 v203, v234, v201
	s_waitcnt lgkmcnt(0)
	v_max3_f32 v206, v192, v201, v203
	v_sub_f32_e32 v192, v192, v206
	v_exp_f32_e32 v192, v192
	s_nop 0
	v_mul_f32_e32 v190, v190, v192
	v_pk_mul_f32 v[106:107], v[106:107], v[192:193] op_sel_hi:[1,0]
	v_pk_mul_f32 v[104:105], v[104:105], v[192:193] op_sel_hi:[1,0]
	v_pk_mul_f32 v[110:111], v[110:111], v[192:193] op_sel_hi:[1,0]
	v_pk_mul_f32 v[108:109], v[108:109], v[192:193] op_sel_hi:[1,0]
	v_pk_mul_f32 v[114:115], v[114:115], v[192:193] op_sel_hi:[1,0]
	v_pk_mul_f32 v[112:113], v[112:113], v[192:193] op_sel_hi:[1,0]
	v_pk_mul_f32 v[122:123], v[122:123], v[192:193] op_sel_hi:[1,0]
	v_pk_mul_f32 v[120:121], v[120:121], v[192:193] op_sel_hi:[1,0]
	v_mov_b64_e32 v[192:193], v[206:207]
	s_branch .LBB0_405

; template <int MODE>
; __device__ __forceinline__ void nsa_compute(int cur, int buf, int t, int hl, u64 mymask, const bf16x8 (&Qf)[2][2], f32x4 (&O)[4][2], float (&m)[2], float (&l)[2],
;                                             const float (&inv)[2], float* impw, char* lds) {
;     ...
; #pragma unroll
;   for (int s2 = 0; s2 < 2; ++s2) {
;     f32x4 S[2][2] = {};
;     bf16x8 kfr[2][2];
; #pragma unroll
;     for (int ks = 0; ks < 2; ++ks)
; #pragma unroll
;       for (int kk = 0; kk < 2; ++kk) kfr[ks][kk] = *(const bf16x8*)(kt + (32 * s2 + 16 * kk + fr) * 128 + (((ks * 4 + fq) ^ (fr & 7)) << 4));
;     __builtin_amdgcn_s_setprio(1);
; #pragma unroll
;     for (int ks = 0; ks < 2; ++ks)
; #pragma unroll
;       for (int kk = 0; kk < 2; ++kk)
; #pragma unroll
;         for (int r = 0; r < 2; ++r) S[kk][r] = mfma16(kfr[ks][kk], Qf[r][ks], S[kk][r]);
;     __builtin_amdgcn_s_setprio(0);
;     bf16x8 Pf[2];
;     float g1s[2] = {0.f, 0.f}, p3s[2] = {0.f, 0.f};
; #pragma unroll
;     for (int r = 0; r < 2; ++r) {
;       float sv[2][4];
; #pragma unroll
;       for (int kk = 0; kk < 2; ++kk)
; #pragma unroll
;         for (int e = 0; e < 4; ++e) {
;           const int off = 32 * s2 + 16 * kk + e;
;           int idx;
;           if (MODE <= 1) { idx = base - 16 * off; idx = idx > 0 ? idx : 0; } else idx = base - off;
;           sv[kk][e] = S[kk][r][e] * (0.125f * LOG2E) + tb[r * TS + idx];
;         }
;       float pv[2][4];
;       if (MODE == 1) {
; #pragma unroll
;         for (int kk = 0; kk < 2; ++kk)
; #pragma unroll
;           for (int e = 0; e < 4; ++e) pv[kk][e] = __builtin_amdgcn_exp2f(sv[kk][e] - m[r]) * inv[r];
; #pragma unroll
;         for (int kk = 0; kk < 2; ++kk) { g1s[kk] += pv[kk][0] + pv[kk][1] + pv[kk][2] + 0.5f * pv[kk][3]; p3s[kk] += 0.5f * pv[kk][3]; }
;       } else {
;         const float mxa = fmaxf(fmaxf(sv[0][0], sv[0][1]), sv[0][2]), mxb = fmaxf(fmaxf(sv[0][3], sv[1][0]), sv[1][1]);
;         float mx = fmaxf(fmaxf(fmaxf(sv[1][2], sv[1][3]), mxa), mxb);
;         if (MODE == 2) mx = selok ? mx : -__builtin_inff();
;         if (__any(mx > m[r] + 8.0f)) {
;           mx = fmaxf(mx, __shfl_xor(mx, 16)); mx = fmaxf(mx, __shfl_xor(mx, 32));
;           const float mn = fmaxf(m[r], mx), al = __builtin_amdgcn_exp2f(m[r] - mn);
;           m[r] = mn; l[r] *= al;
;           if (MODE != 0) {
; #pragma unroll
.LBB0_452:
	v_add_f32_e32 v16, 0, v37
	v_add_f32_e32 v16, v38, v16
	v_add_f32_e32 v16, v39, v16
	v_add_f32_e32 v16, v40, v16
	v_add_f32_e32 v16, v41, v16
	v_add_f32_e32 v16, v42, v16
	v_add_f32_e32 v16, v43, v16
	v_add_f32_e32 v16, v36, v16
	s_cmp_lt_i32 s16, 0
	v_add_f32_e32 v145, v145, v16
	s_cbranch_scc1 .LBB0_435
	s_lshl_b64 s[30:31], 1, s16
	v_mov_b32 v18, v179
	v_and_b32_e32 v17, s31, v187
	v_lshrrev_b32_e32 v19, 4, v18
	v_bfe_u32 v24, v18, 4, 2
	v_and_b32_e32 v16, s30, v186
	v_and_b32_e32 v25, 7, v18
	v_and_b32_e32 v117, 15, v18
	s_lshl_b32 s72, s74, 13
	v_cmp_eq_u64_e64 s[36:37], 0, v[16:17]
	v_lshlrev_b32_e32 v118, 2, v24
	v_bitop3_b32 v16, v19, v25, 3 bitop3:0x6c
	v_bitop3_b32 v24, v24, v25, 4 bitop3:0x36
	v_lshlrev_b32_e32 v114, 7, v117
	v_lshl_or_b32 v115, v16, 4, s72
	v_lshl_or_b32 v116, v24, 4, s72
	v_or_b32_e32 v20, v115, v114
	v_or_b32_e32 v28, v116, v114
	ds_read_b128 v[16:19], v20
	ds_read_b128 v[20:23], v20 offset:2048
	ds_read_b128 v[24:27], v28
	ds_read_b128 v[28:31], v28 offset:2048
	v_sub_u32_e32 v251, v180, v118
	v_lshl_add_u32 v251, v251, 2, v181
	s_lshl_b32 s16, s16, 8
	v_subrev_u32_e32 v250, s16, v251
	v_add_u32_e32 v249, 0x8400, v250
	v_add_u32_e32 v248, 0xc500, v250
	ds_read2_b32 v[148:149], v249 offset0:63 offset1:64
	ds_read2_b32 v[150:151], v249 offset0:61 offset1:62
	ds_read2_b32 v[152:153], v249 offset0:47 offset1:48
	ds_read2_b32 v[154:155], v249 offset0:45 offset1:46
	ds_read2_b32 v[156:157], v248 offset0:63 offset1:64
	ds_read2_b32 v[168:169], v248 offset0:61 offset1:62
	ds_read2_b32 v[170:171], v248 offset0:47 offset1:48
	ds_read2_b32 v[172:173], v248 offset0:45 offset1:46
	s_setprio 1
	s_waitcnt lgkmcnt(11)
	v_mfma_f32_16x16x32_bf16 v[32:35], v[16:19], v[0:3], 0
	v_mfma_f32_16x16x32_bf16 v[16:19], v[16:19], v[8:11], 0
	s_waitcnt lgkmcnt(10)
	v_mfma_f32_16x16x32_bf16 v[40:43], v[20:23], v[0:3], 0
	v_mfma_f32_16x16x32_bf16 v[20:23], v[20:23], v[8:11], 0
	s_waitcnt lgkmcnt(9)
	v_mfma_f32_16x16x32_bf16 v[36:39], v[24:27], v[12:15], v[16:19]
	s_waitcnt lgkmcnt(8)
	v_mfma_f32_16x16x32_bf16 v[16:19], v[28:31], v[4:7], v[40:43]
	v_mfma_f32_16x16x32_bf16 v[28:31], v[28:31], v[12:15], v[20:23]
	v_mfma_f32_16x16x32_bf16 v[32:35], v[24:27], v[4:7], v[32:35]
	s_setprio 0
	s_nop 0
	v_sub_u32_e32 v20, v180, v118
	v_lshl_add_u32 v20, v20, 2, v181
	v_subrev_u32_e32 v122, s16, v20
	s_waitcnt lgkmcnt(7)
	s_nop 1
	v_fmamk_f32 v47, v32, 0x3e38aa3b, v149
	v_fmamk_f32 v46, v33, 0x3e38aa3b, v148
	s_waitcnt lgkmcnt(6)
	v_fmamk_f32 v43, v34, 0x3e38aa3b, v151
	v_fmamk_f32 v42, v35, 0x3e38aa3b, v150
	s_waitcnt lgkmcnt(5)
	v_fmamk_f32 v41, v16, 0x3e38aa3b, v153
	v_fmamk_f32 v40, v17, 0x3e38aa3b, v152
	v_max3_f32 v16, v47, v46, v43
	v_max3_f32 v17, v42, v41, v40
	s_waitcnt lgkmcnt(4)
	v_fmamk_f32 v45, v18, 0x3e38aa3b, v155
	v_fmamk_f32 v44, v19, 0x3e38aa3b, v154
	v_max_f32_e32 v18, v45, v44
	v_max3_f32 v16, v18, v16, v17
	v_cndmask_b32_e64 v16, v16, v225, s[36:37]
	v_add_f32_e32 v17, 0x41000000, v188
	v_cmp_gt_f32_e32 vcc, v16, v17
	s_cbranch_vccz .LBB0_455
	ds_bpermute_b32 v17, v233, v16
	v_max_f32_e32 v16, v16, v16
	v_mov_b32_e32 v105, v189
	v_mov_b32_e32 v147, v145
	s_waitcnt lgkmcnt(0)
	v_max_f32_e32 v17, v17, v17
	v_max_f32_e32 v16, v16, v17
	ds_bpermute_b32 v17, v234, v16
	s_waitcnt lgkmcnt(0)
	v_max3_f32 v104, v188, v16, v17
	v_sub_f32_e32 v16, v188, v104
	v_exp_f32_e32 v32, v16
	v_mov_b64_e32 v[188:189], v[104:105]
	v_mul_f32_e32 v146, v144, v32
	v_pk_mul_f32 v[90:91], v[90:91], v[32:33] op_sel_hi:[1,0]
	v_pk_mul_f32 v[88:89], v[88:89], v[32:33] op_sel_hi:[1,0]
	v_pk_mul_f32 v[102:103], v[102:103], v[32:33] op_sel_hi:[1,0]
	v_pk_mul_f32 v[100:101], v[100:101], v[32:33] op_sel_hi:[1,0]
	v_pk_mul_f32 v[94:95], v[94:95], v[32:33] op_sel_hi:[1,0]
	v_pk_mul_f32 v[92:93], v[92:93], v[32:33] op_sel_hi:[1,0]
	v_pk_mul_f32 v[82:83], v[82:83], v[32:33] op_sel_hi:[1,0]
	v_pk_mul_f32 v[80:81], v[80:81], v[32:33] op_sel_hi:[1,0]
	s_branch .LBB0_456
.LBB0_455:
	v_mov_b64_e32 v[146:147], v[144:145]
.LBB0_456:
	v_cndmask_b32_e64 v104, v188, v228, s[36:37]
	v_sub_f32_e32 v47, v47, v104
	v_exp_f32_e32 v119, v47
	v_sub_f32_e32 v46, v46, v104
	v_exp_f32_e32 v120, v46
	v_sub_f32_e32 v43, v43, v104
	v_exp_f32_e32 v121, v43
	v_sub_f32_e32 v42, v42, v104
	v_exp_f32_e32 v123, v42
	v_sub_f32_e32 v41, v41, v104
	v_add_f32_e32 v47, 0, v119
	v_exp_f32_e32 v124, v41
	v_sub_f32_e32 v40, v40, v104
	v_add_f32_e32 v46, v120, v47
	v_exp_f32_e32 v125, v40
	v_add_f32_e32 v43, v121, v46
	v_add_f32_e32 v42, v123, v43
	v_add_f32_e32 v41, v124, v42
	v_add_f32_e32 v40, v125, v41
	v_sub_f32_e32 v41, v45, v104
	v_exp_f32_e32 v126, v41
	v_sub_f32_e32 v41, v44, v104
	v_exp_f32_e32 v127, v41
	v_add_f32_e32 v40, v126, v40
	v_add_f32_e32 v40, v127, v40
	v_add_f32_e32 v146, v146, v40
	s_waitcnt lgkmcnt(3)
	v_fmamk_f32 v47, v36, 0x3e38aa3b, v157
	v_fmamk_f32 v46, v37, 0x3e38aa3b, v156
	s_waitcnt lgkmcnt(2)
	v_fmamk_f32 v113, v38, 0x3e38aa3b, v169
	v_fmamk_f32 v112, v39, 0x3e38aa3b, v168
	s_waitcnt lgkmcnt(1)
	v_fmamk_f32 v45, v28, 0x3e38aa3b, v171
	v_fmamk_f32 v44, v29, 0x3e38aa3b, v170
	s_waitcnt lgkmcnt(0)
	v_fmamk_f32 v29, v30, 0x3e38aa3b, v173
	v_fmamk_f32 v28, v31, 0x3e38aa3b, v172
	v_max3_f32 v30, v47, v46, v113
	v_max3_f32 v31, v112, v45, v44
	v_max_f32_e32 v36, v29, v28
	v_max3_f32 v30, v36, v30, v31
	v_cndmask_b32_e64 v30, v30, v225, s[36:37]
	v_add_f32_e32 v31, 0x41000000, v189
	v_cmp_gt_f32_e32 vcc, v30, v31
	s_cbranch_vccz .LBB0_458
	ds_bpermute_b32 v31, v233, v30
	v_max_f32_e32 v30, v30, v30
	s_waitcnt lgkmcnt(0)
	v_max_f32_e32 v31, v31, v31
	v_max_f32_e32 v30, v30, v31
	ds_bpermute_b32 v31, v234, v30
	s_waitcnt lgkmcnt(0)
	v_max3_f32 v30, v189, v30, v31
	v_sub_f32_e32 v31, v189, v30
	v_exp_f32_e32 v108, v31
	v_mov_b32_e32 v189, v30
	v_mul_f32_e32 v147, v147, v108
	v_pk_mul_f32 v[98:99], v[98:99], v[108:109] op_sel_hi:[1,0]
	v_pk_mul_f32 v[96:97], v[96:97], v[108:109] op_sel_hi:[1,0]
	v_pk_mul_f32 v[86:87], v[86:87], v[108:109] op_sel_hi:[1,0]
	v_pk_mul_f32 v[84:85], v[84:85], v[108:109] op_sel_hi:[1,0]
	v_pk_mul_f32 v[78:79], v[78:79], v[108:109] op_sel_hi:[1,0]
	v_pk_mul_f32 v[76:77], v[76:77], v[108:109] op_sel_hi:[1,0]
	v_pk_mul_f32 v[74:75], v[74:75], v[108:109] op_sel_hi:[1,0]
	v_pk_mul_f32 v[72:73], v[72:73], v[108:109] op_sel_hi:[1,0]
	s_branch .LBB0_459
; template <int MODE>
; __device__ __forceinline__ void nsa_compute(int cur, int buf, int t, int hl, u64 mymask, const bf16x8 (&Qf)[2][2], f32x4 (&O)[4][2], float (&m)[2], float (&l)[2],
;                                             const float (&inv)[2], float* impw, char* lds) {
;     ...
; #pragma unroll
;     for (int ks = 0; ks < 2; ++ks)
; #pragma unroll
;       for (int kk = 0; kk < 2; ++kk) kfr[ks][kk] = *(const bf16x8*)(kt + (32 * s2 + 16 * kk + fr) * 128 + (((ks * 4 + fq) ^ (fr & 7)) << 4));
;     __builtin_amdgcn_s_setprio(1);
; #pragma unroll
;     for (int ks = 0; ks < 2; ++ks)
; #pragma unroll
;       for (int kk = 0; kk < 2; ++kk)
; #pragma unroll
;         for (int r = 0; r < 2; ++r) S[kk][r] = mfma16(kfr[ks][kk], Qf[r][ks], S[kk][r]);
;     __builtin_amdgcn_s_setprio(0);
;     bf16x8 Pf[2];
;     float g1s[2] = {0.f, 0.f}, p3s[2] = {0.f, 0.f};
; #pragma unroll
;     for (int r = 0; r < 2; ++r) {
;       float sv[2][4];
; #pragma unroll
;       for (int kk = 0; kk < 2; ++kk)
; #pragma unroll
;         for (int e = 0; e < 4; ++e) {
;     ...
;         const float me = (MODE == 2) ? (selok ? m[r] : __builtin_inff()) : m[r];
;         float ps = 0.f;
; #pragma unroll
;         for (int kk = 0; kk < 2; ++kk)
; #pragma unroll
;           for (int e = 0; e < 4; ++e) { pv[kk][e] = __builtin_amdgcn_exp2f(sv[kk][e] - me); ps += pv[kk][e]; }
;         l[r] += ps;
;       }
;       if (MODE != 0) {
;         const unsigned w0 = pk2(pv[0][0], pv[0][1]), w1 = pk2(pv[0][2], pv[0][3]), w2 = pk2(pv[1][0], pv[1][1]), w3 = pk2(pv[1][2], pv[1][3]);
;         u32x4 pw; pw.x = w0; pw.y = w1; pw.z = w2; pw.w = w3;
;         Pf[r] = __builtin_bit_cast(bf16x8, pw);
;       }
;     }
;     if (MODE != 0) {
;       bf16x8 vfr[4];
; #pragma unroll
;       for (int df = 0; df < 4; ++df) {
;         const bf16x4 va = *(const bf16x4*)(vt + (df * 16 + fr) * 68 + 32 * s2 + 4 * fq);
;         const bf16x4 vb = *(const bf16x4*)(vt + (df * 16 + fr) * 68 + 32 * s2 + 16 + 4 * fq);
;         bf16x8 vf; vf[0] = va[0]; vf[1] = va[1]; vf[2] = va[2]; vf[3] = va[3]; vf[4] = vb[0]; vf[5] = vb[1]; vf[6] = vb[2]; vf[7] = vb[3];
;         vfr[df] = vf;
;       }
;       __builtin_amdgcn_s_setprio(1);
; #pragma unroll
;       for (int df = 0; df < 4; ++df)
; #pragma unroll
;         for (int r = 0; r < 2; ++r) O[df][r] = mfma16(vfr[df], Pf[r], O[df][r]);
;       __builtin_amdgcn_s_setprio(0);
.LBB0_458:
.LBB0_459:
	v_cndmask_b32_e64 v30, v189, v228, s[36:37]
	v_sub_f32_e32 v31, v47, v30
	v_exp_f32_e32 v31, v31
	v_sub_f32_e32 v46, v46, v30
	v_exp_f32_e32 v46, v46
	v_sub_f32_e32 v113, v113, v30
	v_exp_f32_e32 v113, v113
	v_sub_f32_e32 v112, v112, v30
	v_exp_f32_e32 v112, v112
	v_sub_f32_e32 v45, v45, v30
	v_exp_f32_e32 v45, v45
	v_sub_f32_e32 v44, v44, v30
	v_add_f32_e32 v47, v46, v31
	v_exp_f32_e32 v44, v44
	v_sub_f32_e32 v29, v29, v30
	v_add_f32_e32 v47, v113, v47
	v_exp_f32_e32 v29, v29
	v_sub_f32_e32 v28, v28, v30
	v_add_f32_e32 v47, v112, v47
	v_exp_f32_e32 v28, v28
	v_add_f32_e32 v47, v45, v47
	v_add_f32_e32 v47, v44, v47
	v_add_f32_e32 v47, v29, v47
	s_lshl_b32 s16, s74, 9
	v_add_f32_e32 v30, v28, v47
	v_cvt_pk_bf16_f32 v135, v29, v28
	v_mul_u32_u24_e32 v28, 0x44, v117
	s_add_i32 s73, s72, s16
	v_lshlrev_b32_e32 v28, 1, v28
	v_lshlrev_b32_e32 v29, 1, v118
	v_add3_u32 v28, s73, v28, v29
	v_cvt_pk_bf16_f32 v129, v121, v123
	v_cvt_pk_bf16_f32 v130, v124, v125
	v_add_u32_e32 v123, 0x4000, v28
	v_add_u32_e32 v124, 0x4800, v28
	v_cvt_pk_bf16_f32 v128, v119, v120
	v_cvt_pk_bf16_f32 v131, v126, v127
	v_cvt_pk_bf16_f32 v132, v31, v46
	v_cvt_pk_bf16_f32 v134, v45, v44
	ds_read2_b64 v[44:47], v123 offset1:4
	ds_read2_b64 v[118:121], v124 offset0:16 offset1:20
	v_add_u32_e32 v125, 0x5000, v28
	v_add_u32_e32 v126, 0x5800, v28
	ds_read2_b64 v[136:139], v125 offset0:32 offset1:36
	ds_read2_b64 v[140:143], v126 offset0:48 offset1:52
	v_add_f32_e32 v147, v147, v30
	v_cvt_pk_bf16_f32 v133, v113, v112
	s_setprio 1
	s_waitcnt lgkmcnt(3)
	v_mfma_f32_16x16x32_bf16 v[28:31], v[44:47], v[128:131], v[88:91]
	v_mfma_f32_16x16x32_bf16 v[44:47], v[44:47], v[132:135], v[96:99]
	s_waitcnt lgkmcnt(2)
	v_mfma_f32_16x16x32_bf16 v[24:27], v[118:121], v[128:131], v[100:103]
	v_mfma_f32_16x16x32_bf16 v[40:43], v[118:121], v[132:135], v[84:87]
	s_waitcnt lgkmcnt(1)
	v_mfma_f32_16x16x32_bf16 v[20:23], v[136:139], v[128:131], v[92:95]
	v_mfma_f32_16x16x32_bf16 v[36:39], v[136:139], v[132:135], v[76:79]
	s_waitcnt lgkmcnt(0)
	v_mfma_f32_16x16x32_bf16 v[16:19], v[140:143], v[128:131], v[80:83]
	v_mfma_f32_16x16x32_bf16 v[32:35], v[140:143], v[132:135], v[72:75]
	s_setprio 0
	s_nop 1
	v_add_u32_e32 v108, v115, v114
	v_add_u32_e32 v116, v116, v114
	ds_read_b128 v[104:107], v108 offset:4096
	ds_read_b128 v[108:111], v108 offset:6144
	ds_read_b128 v[112:115], v116 offset:4096
	ds_read_b128 v[116:119], v116 offset:6144
	v_add_u32_e32 v251, 0x8400, v122
	v_add_u32_e32 v250, 0xc500, v122
	ds_read2_b32 v[152:153], v251 offset0:31 offset1:32
	ds_read2_b32 v[154:155], v251 offset0:29 offset1:30
	ds_read2_b32 v[156:157], v251 offset0:15 offset1:16
	ds_read2_b32 v[168:169], v251 offset0:13 offset1:14
	ds_read2_b32 v[170:171], v250 offset0:31 offset1:32
	ds_read2_b32 v[172:173], v250 offset0:29 offset1:30
	ds_read2_b32 v[174:175], v250 offset0:15 offset1:16
	ds_read2_b32 v[192:193], v250 offset0:13 offset1:14
	s_setprio 1
	s_waitcnt lgkmcnt(11)
	v_mfma_f32_16x16x32_bf16 v[128:131], v[104:107], v[0:3], 0
	v_mfma_f32_16x16x32_bf16 v[104:107], v[104:107], v[8:11], 0
	s_waitcnt lgkmcnt(10)
	v_mfma_f32_16x16x32_bf16 v[136:139], v[108:111], v[8:11], 0
	v_mfma_f32_16x16x32_bf16 v[132:135], v[108:111], v[0:3], 0
	s_waitcnt lgkmcnt(9)
	v_mfma_f32_16x16x32_bf16 v[128:131], v[112:115], v[4:7], v[128:131]
	v_mfma_f32_16x16x32_bf16 v[108:111], v[112:115], v[12:15], v[104:107]
	s_waitcnt lgkmcnt(8)
	v_mfma_f32_16x16x32_bf16 v[104:107], v[116:119], v[12:15], v[136:139]
	v_mfma_f32_16x16x32_bf16 v[132:135], v[116:119], v[4:7], v[132:135]
	s_setprio 0
	s_waitcnt lgkmcnt(7)
	s_nop 1
	v_fmamk_f32 v127, v128, 0x3e38aa3b, v153
	v_fmamk_f32 v116, v129, 0x3e38aa3b, v152
	s_waitcnt lgkmcnt(6)
	v_fmamk_f32 v117, v130, 0x3e38aa3b, v155
	v_fmamk_f32 v114, v131, 0x3e38aa3b, v154
	s_waitcnt lgkmcnt(5)
	v_fmamk_f32 v113, v132, 0x3e38aa3b, v157
	v_fmamk_f32 v112, v133, 0x3e38aa3b, v156
	v_max3_f32 v115, v127, v116, v117
	s_waitcnt lgkmcnt(4)
	v_fmamk_f32 v128, v134, 0x3e38aa3b, v169
	v_fmamk_f32 v118, v135, 0x3e38aa3b, v168
	v_max3_f32 v119, v114, v113, v112
	v_max_f32_e32 v120, v128, v118
	v_max3_f32 v115, v120, v115, v119
	v_cndmask_b32_e64 v115, v115, v225, s[36:37]
	v_add_f32_e32 v119, 0x41000000, v188
	v_cmp_gt_f32_e32 vcc, v115, v119
	s_cbranch_vccz .LBB0_461
	ds_bpermute_b32 v119, v233, v115
	v_max_f32_e32 v115, v115, v115
	v_mov_b32_e32 v121, v189
	s_waitcnt lgkmcnt(0)
	v_max_f32_e32 v119, v119, v119
	v_max_f32_e32 v115, v115, v119
	ds_bpermute_b32 v119, v234, v115
	s_waitcnt lgkmcnt(0)
	v_max3_f32 v120, v188, v115, v119
	v_sub_f32_e32 v115, v188, v120
	v_exp_f32_e32 v130, v115
	v_mov_b64_e32 v[188:189], v[120:121]
	v_mul_f32_e32 v146, v146, v130
	v_pk_mul_f32 v[30:31], v[30:31], v[130:131] op_sel_hi:[1,0]
	v_pk_mul_f32 v[28:29], v[28:29], v[130:131] op_sel_hi:[1,0]
	v_pk_mul_f32 v[26:27], v[26:27], v[130:131] op_sel_hi:[1,0]
	v_pk_mul_f32 v[24:25], v[24:25], v[130:131] op_sel_hi:[1,0]
	v_pk_mul_f32 v[22:23], v[22:23], v[130:131] op_sel_hi:[1,0]
	v_pk_mul_f32 v[20:21], v[20:21], v[130:131] op_sel_hi:[1,0]
	v_pk_mul_f32 v[18:19], v[18:19], v[130:131] op_sel_hi:[1,0]
	v_pk_mul_f32 v[16:17], v[16:17], v[130:131] op_sel_hi:[1,0]
	s_branch .LBB0_462

; template <int MODE>
; __device__ __forceinline__ void nsa_compute(int cur, int buf, int t, int hl, u64 mymask, const bf16x8 (&Qf)[2][2], f32x4 (&O)[4][2], float (&m)[2], float (&l)[2],
;                                             const float (&inv)[2], float* impw, char* lds) {
;     ...
; #pragma unroll
;   for (int s2 = 0; s2 < 2; ++s2) {
;     f32x4 S[2][2] = {};
;     bf16x8 kfr[2][2];
; #pragma unroll
;     for (int ks = 0; ks < 2; ++ks)
; #pragma unroll
;       for (int kk = 0; kk < 2; ++kk) kfr[ks][kk] = *(const bf16x8*)(kt + (32 * s2 + 16 * kk + fr) * 128 + (((ks * 4 + fq) ^ (fr & 7)) << 4));
;     __builtin_amdgcn_s_setprio(1);
; #pragma unroll
;     for (int ks = 0; ks < 2; ++ks)
; #pragma unroll
;       for (int kk = 0; kk < 2; ++kk)
; #pragma unroll
;         for (int r = 0; r < 2; ++r) S[kk][r] = mfma16(kfr[ks][kk], Qf[r][ks], S[kk][r]);
;     __builtin_amdgcn_s_setprio(0);
;     bf16x8 Pf[2];
;     float g1s[2] = {0.f, 0.f}, p3s[2] = {0.f, 0.f};
; #pragma unroll
;     for (int r = 0; r < 2; ++r) {
;       float sv[2][4];
; #pragma unroll
;       for (int kk = 0; kk < 2; ++kk)
; #pragma unroll
;         for (int e = 0; e < 4; ++e) {
;           const int off = 32 * s2 + 16 * kk + e;
;           int idx;
;           if (MODE <= 1) { idx = base - 16 * off; idx = idx > 0 ? idx : 0; } else idx = base - off;
;           sv[kk][e] = S[kk][r][e] * (0.125f * LOG2E) + tb[r * TS + idx];
;         }
;       float pv[2][4];
;       if (MODE == 1) {
; #pragma unroll
;         for (int kk = 0; kk < 2; ++kk)
; #pragma unroll
;           for (int e = 0; e < 4; ++e) pv[kk][e] = __builtin_amdgcn_exp2f(sv[kk][e] - m[r]) * inv[r];
; #pragma unroll
;         for (int kk = 0; kk < 2; ++kk) { g1s[kk] += pv[kk][0] + pv[kk][1] + pv[kk][2] + 0.5f * pv[kk][3]; p3s[kk] += 0.5f * pv[kk][3]; }
;       } else {
;         const float mxa = fmaxf(fmaxf(sv[0][0], sv[0][1]), sv[0][2]), mxb = fmaxf(fmaxf(sv[0][3], sv[1][0]), sv[1][1]);
;         float mx = fmaxf(fmaxf(fmaxf(sv[1][2], sv[1][3]), mxa), mxb);
;         if (MODE == 2) mx = selok ? mx : -__builtin_inff();
;         if (__any(mx > m[r] + 8.0f)) {
;           mx = fmaxf(mx, __shfl_xor(mx, 16)); mx = fmaxf(mx, __shfl_xor(mx, 32));
;           const float mn = fmaxf(m[r], mx), al = __builtin_amdgcn_exp2f(m[r] - mn);
;           m[r] = mn; l[r] *= al;
;           if (MODE != 0) {
; #pragma unroll
.LBB0_469:
	v_add_f32_e32 v16, 0, v136
	v_add_f32_e32 v16, v137, v16
	v_add_f32_e32 v16, v138, v16
	v_add_f32_e32 v16, v139, v16
	v_add_f32_e32 v16, v140, v16
	v_add_f32_e32 v16, v141, v16
	v_add_f32_e32 v16, v142, v16
	v_add_f32_e32 v16, v143, v16
	v_add_f32_e32 v147, v147, v16
	s_mov_b64 s[36:37], -1
	s_cmp_lt_i32 s62, 0
	s_mov_b64 vcc, -1
	s_cbranch_scc1 .LBB0_487
	s_lshl_b64 s[36:37], 1, s62
	v_mov_b32 v18, v179
	v_and_b32_e32 v17, s37, v187
	v_lshrrev_b32_e32 v19, 4, v18
	v_bfe_u32 v24, v18, 4, 2
	v_and_b32_e32 v16, s36, v186
	v_and_b32_e32 v25, 7, v18
	v_and_b32_e32 v150, 15, v18
	v_cmp_eq_u64_e64 s[36:37], 0, v[16:17]
	v_lshlrev_b32_e32 v151, 2, v24
	v_bitop3_b32 v16, v19, v25, 3 bitop3:0x6c
	v_bitop3_b32 v24, v24, v25, 4 bitop3:0x36
	v_lshlrev_b32_e32 v26, 7, v150
	v_lshl_add_u32 v16, v16, 4, s63
	v_lshl_add_u32 v24, v24, 4, s63
	v_add_u32_e32 v148, v16, v26
	v_add_u32_e32 v149, v24, v26
	ds_read_b128 v[16:19], v148
	ds_read_b128 v[20:23], v148 offset:2048
	ds_read_b128 v[24:27], v149
	ds_read_b128 v[32:35], v149 offset:2048
	v_sub_u32_e32 v251, v180, v151
	v_lshl_add_u32 v251, v251, 2, v181
	s_lshl_b32 s16, s62, 8
	v_subrev_u32_e32 v250, s16, v251
	v_add_u32_e32 v249, 0x8400, v250
	v_add_u32_e32 v248, 0xc500, v250
	ds_read2_b32 v[192:193], v249 offset0:63 offset1:64
	ds_read2_b32 v[194:195], v249 offset0:61 offset1:62
	ds_read2_b32 v[198:199], v249 offset0:47 offset1:48
	ds_read2_b32 v[200:201], v249 offset0:45 offset1:46
	ds_read2_b32 v[202:203], v248 offset0:63 offset1:64
	ds_read2_b32 v[204:205], v248 offset0:61 offset1:62
	ds_read2_b32 v[206:207], v248 offset0:47 offset1:48
	ds_read2_b32 v[208:209], v248 offset0:45 offset1:46
	s_setprio 1
	s_waitcnt lgkmcnt(11)
	v_mfma_f32_16x16x32_bf16 v[28:31], v[16:19], v[0:3], 0
	v_mfma_f32_16x16x32_bf16 v[16:19], v[16:19], v[8:11], 0
	s_waitcnt lgkmcnt(10)
	v_mfma_f32_16x16x32_bf16 v[36:39], v[20:23], v[0:3], 0
	v_mfma_f32_16x16x32_bf16 v[20:23], v[20:23], v[8:11], 0
	s_waitcnt lgkmcnt(9)
	v_mfma_f32_16x16x32_bf16 v[40:43], v[24:27], v[4:7], v[28:31]
	v_mfma_f32_16x16x32_bf16 v[28:31], v[24:27], v[12:15], v[16:19]
	s_waitcnt lgkmcnt(8)
	v_mfma_f32_16x16x32_bf16 v[16:19], v[32:35], v[4:7], v[36:39]
	v_mfma_f32_16x16x32_bf16 v[20:23], v[32:35], v[12:15], v[20:23]
	s_setprio 0
	v_sub_u32_e32 v24, v180, v151
	v_lshl_add_u32 v24, v24, 2, v181
	v_subrev_u32_e32 v158, s16, v24
	s_waitcnt lgkmcnt(7)
	v_fmamk_f32 v47, v40, 0x3e38aa3b, v193
	v_fmamk_f32 v46, v41, 0x3e38aa3b, v192
	s_waitcnt lgkmcnt(6)
	v_fmamk_f32 v39, v42, 0x3e38aa3b, v195
	v_fmamk_f32 v38, v43, 0x3e38aa3b, v194
	s_waitcnt lgkmcnt(5)
	v_fmamk_f32 v37, v16, 0x3e38aa3b, v199
	v_fmamk_f32 v36, v17, 0x3e38aa3b, v198
	v_max3_f32 v16, v47, v46, v39
	v_max3_f32 v17, v38, v37, v36
	s_waitcnt lgkmcnt(4)
	v_fmamk_f32 v45, v18, 0x3e38aa3b, v201
	v_fmamk_f32 v44, v19, 0x3e38aa3b, v200
	v_max_f32_e32 v18, v45, v44
	v_max3_f32 v16, v18, v16, v17
	v_cndmask_b32_e64 v16, v16, v225, s[36:37]
	v_add_f32_e32 v17, 0x41000000, v188
	v_cmp_gt_f32_e32 vcc, v16, v17
	s_cbranch_vccz .LBB0_472
	ds_bpermute_b32 v17, v233, v16
	v_max_f32_e32 v16, v16, v16
	v_mov_b32_e32 v137, v189
	v_mov_b32_e32 v191, v147
	s_waitcnt lgkmcnt(0)
	v_max_f32_e32 v17, v17, v17
	v_max_f32_e32 v16, v16, v17
	ds_bpermute_b32 v17, v234, v16
	s_waitcnt lgkmcnt(0)
	v_max3_f32 v136, v188, v16, v17
	v_sub_f32_e32 v16, v188, v136
	v_exp_f32_e32 v40, v16
	v_mov_b64_e32 v[188:189], v[136:137]
	v_mul_f32_e32 v190, v146, v40
	v_pk_mul_f32 v[106:107], v[106:107], v[40:41] op_sel_hi:[1,0]
	v_pk_mul_f32 v[104:105], v[104:105], v[40:41] op_sel_hi:[1,0]
	v_pk_mul_f32 v[126:127], v[126:127], v[40:41] op_sel_hi:[1,0]
	v_pk_mul_f32 v[124:125], v[124:125], v[40:41] op_sel_hi:[1,0]
	v_pk_mul_f32 v[130:131], v[130:131], v[40:41] op_sel_hi:[1,0]
	v_pk_mul_f32 v[128:129], v[128:129], v[40:41] op_sel_hi:[1,0]
	v_pk_mul_f32 v[134:135], v[134:135], v[40:41] op_sel_hi:[1,0]
	v_pk_mul_f32 v[132:133], v[132:133], v[40:41] op_sel_hi:[1,0]
	s_branch .LBB0_473
.LBB0_472:
	v_mov_b64_e32 v[190:191], v[146:147]
.LBB0_473:
	v_cndmask_b32_e64 v136, v188, v228, s[36:37]
	v_sub_f32_e32 v47, v47, v136
	v_exp_f32_e32 v152, v47
	v_sub_f32_e32 v46, v46, v136
	v_exp_f32_e32 v153, v46
	v_sub_f32_e32 v39, v39, v136
	v_exp_f32_e32 v154, v39
	v_sub_f32_e32 v38, v38, v136
	v_exp_f32_e32 v155, v38
	v_sub_f32_e32 v37, v37, v136
	v_add_f32_e32 v47, 0, v152
	v_exp_f32_e32 v156, v37
	v_sub_f32_e32 v36, v36, v136
	v_add_f32_e32 v46, v153, v47
	v_exp_f32_e32 v157, v36
	v_add_f32_e32 v39, v154, v46
	v_add_f32_e32 v38, v155, v39
	v_add_f32_e32 v37, v156, v38
	v_add_f32_e32 v36, v157, v37
	v_sub_f32_e32 v37, v45, v136
	v_exp_f32_e32 v159, v37
	v_sub_f32_e32 v37, v44, v136
	v_exp_f32_e32 v160, v37
	v_add_f32_e32 v36, v159, v36
	v_add_f32_e32 v36, v160, v36
	v_add_f32_e32 v190, v190, v36
	s_waitcnt lgkmcnt(3)
	v_fmamk_f32 v139, v28, 0x3e38aa3b, v203
	v_fmamk_f32 v138, v29, 0x3e38aa3b, v202
	s_waitcnt lgkmcnt(2)
	v_fmamk_f32 v141, v30, 0x3e38aa3b, v205
	v_fmamk_f32 v140, v31, 0x3e38aa3b, v204
	s_waitcnt lgkmcnt(1)
	v_fmamk_f32 v137, v20, 0x3e38aa3b, v207
	v_fmamk_f32 v136, v21, 0x3e38aa3b, v206
	v_max3_f32 v20, v139, v138, v141
	v_max3_f32 v21, v140, v137, v136
	s_waitcnt lgkmcnt(0)
	v_fmamk_f32 v143, v22, 0x3e38aa3b, v209
	v_fmamk_f32 v142, v23, 0x3e38aa3b, v208
	v_max_f32_e32 v22, v143, v142
	v_max3_f32 v20, v22, v20, v21
	v_cndmask_b32_e64 v20, v20, v225, s[36:37]
	v_add_f32_e32 v21, 0x41000000, v189
	v_cmp_gt_f32_e32 vcc, v20, v21
	s_cbranch_vccz .LBB0_475
	ds_bpermute_b32 v21, v233, v20
	v_max_f32_e32 v20, v20, v20
	s_waitcnt lgkmcnt(0)
	v_max_f32_e32 v21, v21, v21
	v_max_f32_e32 v20, v20, v21
	ds_bpermute_b32 v21, v234, v20
	s_waitcnt lgkmcnt(0)
	v_max3_f32 v161, v189, v20, v21
	v_sub_f32_e32 v20, v189, v161
	v_exp_f32_e32 v44, v20
	v_mov_b32_e32 v189, v161
	v_mul_f32_e32 v191, v191, v44
	v_pk_mul_f32 v[110:111], v[110:111], v[44:45] op_sel_hi:[1,0]
	v_pk_mul_f32 v[108:109], v[108:109], v[44:45] op_sel_hi:[1,0]
	v_pk_mul_f32 v[114:115], v[114:115], v[44:45] op_sel_hi:[1,0]
	v_pk_mul_f32 v[112:113], v[112:113], v[44:45] op_sel_hi:[1,0]
	v_pk_mul_f32 v[118:119], v[118:119], v[44:45] op_sel_hi:[1,0]
	v_pk_mul_f32 v[116:117], v[116:117], v[44:45] op_sel_hi:[1,0]
	v_pk_mul_f32 v[122:123], v[122:123], v[44:45] op_sel_hi:[1,0]
	v_pk_mul_f32 v[120:121], v[120:121], v[44:45] op_sel_hi:[1,0]
	s_branch .LBB0_476
; template <int MODE>
; __device__ __forceinline__ void nsa_compute(int cur, int buf, int t, int hl, u64 mymask, const bf16x8 (&Qf)[2][2], f32x4 (&O)[4][2], float (&m)[2], float (&l)[2],
;                                             const float (&inv)[2], float* impw, char* lds) {
;     ...
; #pragma unroll
;     for (int ks = 0; ks < 2; ++ks)
; #pragma unroll
;       for (int kk = 0; kk < 2; ++kk) kfr[ks][kk] = *(const bf16x8*)(kt + (32 * s2 + 16 * kk + fr) * 128 + (((ks * 4 + fq) ^ (fr & 7)) << 4));
;     __builtin_amdgcn_s_setprio(1);
; #pragma unroll
;     for (int ks = 0; ks < 2; ++ks)
; #pragma unroll
;       for (int kk = 0; kk < 2; ++kk)
; #pragma unroll
;         for (int r = 0; r < 2; ++r) S[kk][r] = mfma16(kfr[ks][kk], Qf[r][ks], S[kk][r]);
;     __builtin_amdgcn_s_setprio(0);
;     bf16x8 Pf[2];
;     float g1s[2] = {0.f, 0.f}, p3s[2] = {0.f, 0.f};
; #pragma unroll
;     for (int r = 0; r < 2; ++r) {
;       float sv[2][4];
; #pragma unroll
;       for (int kk = 0; kk < 2; ++kk)
; #pragma unroll
;         for (int e = 0; e < 4; ++e) {
;     ...
;         const float me = (MODE == 2) ? (selok ? m[r] : __builtin_inff()) : m[r];
;         float ps = 0.f;
; #pragma unroll
;         for (int kk = 0; kk < 2; ++kk)
; #pragma unroll
;           for (int e = 0; e < 4; ++e) { pv[kk][e] = __builtin_amdgcn_exp2f(sv[kk][e] - me); ps += pv[kk][e]; }
;         l[r] += ps;
;       }
;       if (MODE != 0) {
;         const unsigned w0 = pk2(pv[0][0], pv[0][1]), w1 = pk2(pv[0][2], pv[0][3]), w2 = pk2(pv[1][0], pv[1][1]), w3 = pk2(pv[1][2], pv[1][3]);
;         u32x4 pw; pw.x = w0; pw.y = w1; pw.z = w2; pw.w = w3;
;         Pf[r] = __builtin_bit_cast(bf16x8, pw);
;       }
;     }
;     if (MODE != 0) {
;       bf16x8 vfr[4];
; #pragma unroll
;       for (int df = 0; df < 4; ++df) {
;         const bf16x4 va = *(const bf16x4*)(vt + (df * 16 + fr) * 68 + 32 * s2 + 4 * fq);
;         const bf16x4 vb = *(const bf16x4*)(vt + (df * 16 + fr) * 68 + 32 * s2 + 16 + 4 * fq);
;         bf16x8 vf; vf[0] = va[0]; vf[1] = va[1]; vf[2] = va[2]; vf[3] = va[3]; vf[4] = vb[0]; vf[5] = vb[1]; vf[6] = vb[2]; vf[7] = vb[3];
;         vfr[df] = vf;
;       }
;       __builtin_amdgcn_s_setprio(1);
; #pragma unroll
;       for (int df = 0; df < 4; ++df)
; #pragma unroll
;         for (int r = 0; r < 2; ++r) O[df][r] = mfma16(vfr[df], Pf[r], O[df][r]);
;       __builtin_amdgcn_s_setprio(0);
.LBB0_475:
.LBB0_476:
	v_cvt_pk_bf16_f32 v152, v152, v153
	v_cvt_pk_bf16_f32 v153, v154, v155
	v_cvt_pk_bf16_f32 v154, v156, v157
	v_cndmask_b32_e64 v156, v189, v228, s[36:37]
	v_sub_f32_e32 v139, v139, v156
	v_exp_f32_e32 v139, v139
	v_sub_f32_e32 v138, v138, v156
	v_exp_f32_e32 v138, v138
	v_sub_f32_e32 v141, v141, v156
	v_exp_f32_e32 v141, v141
	v_sub_f32_e32 v140, v140, v156
	v_exp_f32_e32 v140, v140
	v_sub_f32_e32 v137, v137, v156
	v_cvt_pk_bf16_f32 v155, v159, v160
	v_exp_f32_e32 v159, v137
	v_add_f32_e32 v157, v138, v139
	v_add_f32_e32 v157, v141, v157
	v_add_f32_e32 v157, v140, v157
	v_sub_f32_e32 v136, v136, v156
	v_add_f32_e32 v137, v159, v157
	v_exp_f32_e32 v157, v136
	s_nop 0
	v_add_f32_e32 v136, v157, v137
	v_sub_f32_e32 v137, v143, v156
	v_exp_f32_e32 v143, v137
	v_sub_f32_e32 v137, v142, v156
	v_exp_f32_e32 v142, v137
	v_cvt_pk_bf16_f32 v137, v141, v140
	v_mul_u32_u24_e32 v140, 0x44, v150
	v_add_f32_e32 v136, v143, v136
	v_lshlrev_b32_e32 v140, 1, v140
	v_lshlrev_b32_e32 v141, 1, v151
	v_add_f32_e32 v136, v142, v136
	v_add3_u32 v150, s71, v140, v141
	v_add_f32_e32 v191, v191, v136
	v_cvt_pk_bf16_f32 v136, v139, v138
	v_cvt_pk_bf16_f32 v138, v159, v157
	v_add_u32_e32 v159, 0x4000, v150
	v_add_u32_e32 v160, 0x4800, v150
	v_cvt_pk_bf16_f32 v139, v143, v142
	ds_read2_b64 v[140:143], v159 offset1:4
	ds_read2_b64 v[164:167], v160 offset0:16 offset1:20
	v_add_u32_e32 v161, 0x5000, v150
	v_add_u32_e32 v162, 0x5800, v150
	ds_read2_b64 v[168:171], v161 offset0:32 offset1:36
	ds_read2_b64 v[172:175], v162 offset0:48 offset1:52
	s_setprio 1
	s_waitcnt lgkmcnt(3)
	v_mfma_f32_16x16x32_bf16 v[16:19], v[140:143], v[152:155], v[104:107]
	v_mfma_f32_16x16x32_bf16 v[20:23], v[140:143], v[136:139], v[108:111]
	s_waitcnt lgkmcnt(2)
	v_mfma_f32_16x16x32_bf16 v[24:27], v[164:167], v[152:155], v[124:127]
	v_mfma_f32_16x16x32_bf16 v[28:31], v[164:167], v[136:139], v[112:115]
	s_waitcnt lgkmcnt(1)
	v_mfma_f32_16x16x32_bf16 v[32:35], v[168:171], v[152:155], v[128:131]
	v_mfma_f32_16x16x32_bf16 v[36:39], v[168:171], v[136:139], v[116:119]
	s_waitcnt lgkmcnt(0)
	v_mfma_f32_16x16x32_bf16 v[40:43], v[172:175], v[152:155], v[132:135]
	v_mfma_f32_16x16x32_bf16 v[44:47], v[172:175], v[136:139], v[120:123]
	s_setprio 0
	ds_read_b128 v[136:139], v148 offset:4096
	ds_read_b128 v[140:143], v148 offset:6144
	ds_read_b128 v[150:153], v149 offset:4096
	ds_read_b128 v[154:157], v149 offset:6144
	v_add_u32_e32 v251, 0x8400, v158
	v_add_u32_e32 v250, 0xc500, v158
	ds_read2_b32 v[192:193], v251 offset0:31 offset1:32
	ds_read2_b32 v[194:195], v251 offset0:29 offset1:30
	ds_read2_b32 v[198:199], v251 offset0:15 offset1:16
	ds_read2_b32 v[200:201], v251 offset0:13 offset1:14
	ds_read2_b32 v[202:203], v250 offset0:31 offset1:32
	ds_read2_b32 v[204:205], v250 offset0:29 offset1:30
	ds_read2_b32 v[206:207], v250 offset0:15 offset1:16
	ds_read2_b32 v[208:209], v250 offset0:13 offset1:14
	s_setprio 1
	s_waitcnt lgkmcnt(11)
	v_mfma_f32_16x16x32_bf16 v[164:167], v[136:139], v[0:3], 0
	v_mfma_f32_16x16x32_bf16 v[136:139], v[136:139], v[8:11], 0
	s_waitcnt lgkmcnt(10)
	v_mfma_f32_16x16x32_bf16 v[172:175], v[140:143], v[8:11], 0
	v_mfma_f32_16x16x32_bf16 v[168:171], v[140:143], v[0:3], 0
	s_waitcnt lgkmcnt(9)
	v_mfma_f32_16x16x32_bf16 v[164:167], v[150:153], v[4:7], v[164:167]
	v_mfma_f32_16x16x32_bf16 v[140:143], v[150:153], v[12:15], v[136:139]
	s_waitcnt lgkmcnt(8)
	v_mfma_f32_16x16x32_bf16 v[136:139], v[154:157], v[12:15], v[172:175]
	v_mfma_f32_16x16x32_bf16 v[168:171], v[154:157], v[4:7], v[168:171]
	s_setprio 0
	s_waitcnt lgkmcnt(7)
	s_nop 1
	v_fmamk_f32 v163, v164, 0x3e38aa3b, v193
	v_fmamk_f32 v152, v165, 0x3e38aa3b, v192
	s_waitcnt lgkmcnt(6)
	v_fmamk_f32 v153, v166, 0x3e38aa3b, v195
	v_fmamk_f32 v150, v167, 0x3e38aa3b, v194
	s_waitcnt lgkmcnt(5)
	v_fmamk_f32 v149, v168, 0x3e38aa3b, v199
	v_fmamk_f32 v148, v169, 0x3e38aa3b, v198
	v_max3_f32 v151, v163, v152, v153
	s_waitcnt lgkmcnt(4)
	v_fmamk_f32 v164, v170, 0x3e38aa3b, v201
	v_fmamk_f32 v154, v171, 0x3e38aa3b, v200
	v_max3_f32 v155, v150, v149, v148
	v_max_f32_e32 v156, v164, v154
	v_max3_f32 v151, v156, v151, v155
	v_cndmask_b32_e64 v151, v151, v225, s[36:37]
	v_add_f32_e32 v155, 0x41000000, v188
	v_cmp_gt_f32_e32 vcc, v151, v155
	s_cbranch_vccz .LBB0_478
	ds_bpermute_b32 v155, v233, v151
	v_max_f32_e32 v151, v151, v151
	v_mov_b32_e32 v157, v189
	s_waitcnt lgkmcnt(0)
	v_max_f32_e32 v155, v155, v155
	v_max_f32_e32 v151, v151, v155
	ds_bpermute_b32 v155, v234, v151
	s_waitcnt lgkmcnt(0)
	v_max3_f32 v156, v188, v151, v155
	v_sub_f32_e32 v151, v188, v156
	v_exp_f32_e32 v166, v151
	v_mov_b64_e32 v[188:189], v[156:157]
	v_mul_f32_e32 v190, v190, v166
	v_pk_mul_f32 v[18:19], v[18:19], v[166:167] op_sel_hi:[1,0]
	v_pk_mul_f32 v[16:17], v[16:17], v[166:167] op_sel_hi:[1,0]
	v_pk_mul_f32 v[26:27], v[26:27], v[166:167] op_sel_hi:[1,0]
	v_pk_mul_f32 v[24:25], v[24:25], v[166:167] op_sel_hi:[1,0]
	v_pk_mul_f32 v[34:35], v[34:35], v[166:167] op_sel_hi:[1,0]
	v_pk_mul_f32 v[32:33], v[32:33], v[166:167] op_sel_hi:[1,0]
	v_pk_mul_f32 v[42:43], v[42:43], v[166:167] op_sel_hi:[1,0]
	v_pk_mul_f32 v[40:41], v[40:41], v[166:167] op_sel_hi:[1,0]
	s_branch .LBB0_479
